# sc1 write-through on GEMM-epilogue and mixer bulk stores (cheaper wbl2 at grid barriers)
# baseline (speedup 1.0000x reference)
.LBB0_172:
	v_lshl_add_u32 v153, s69, 8, v3
	v_and_b32_e32 v145, 0x7cf, v153
	v_lshl_add_u32 v147, v145, 2, s92
	v_bitop3_b32 v145, v153, s5, 16 bitop3:0xc8
	v_lshl_add_u32 v149, v145, 2, s92
	v_bitop3_b32 v145, v153, s8, 32 bitop3:0xc8
	v_lshl_add_u32 v150, v145, 2, s92
	v_bitop3_b32 v145, v153, s9, 48 bitop3:0xc8
	v_add_u32_e32 v176, 0x80, v153
	v_lshl_add_u32 v151, v145, 2, s92
	v_and_b32_e32 v145, 0x7cf, v176
	v_add_u32_e32 v148, 0x90, v153
	v_lshl_add_u32 v152, v145, 2, s92
	v_and_b32_e32 v145, 0x7df, v148
	v_add_u32_e32 v146, 0xa0, v153
	v_lshl_add_u32 v154, v145, 2, s92
	v_and_b32_e32 v145, 0x7ef, v146
	v_lshl_add_u32 v172, v145, 2, s92
	v_add_u32_e32 v145, 0xb0, v153
	v_and_b32_e32 v173, 0x7ff, v145
	v_lshl_add_u32 v173, v173, 2, s92
	ds_read_b32 v177, v147
	ds_read_b32 v178, v149
	ds_read_b32 v179, v150
	ds_read_b32 v180, v151
	ds_read_b32 v181, v152
	ds_read_b32 v182, v154
	ds_read_b32 v149, v172
	ds_read_b32 v147, v173
	s_waitcnt lgkmcnt(0)
	v_mul_f32_e32 v152, 0xbfb8aa3b, v177
	v_pk_mul_f32 v[172:173], v[128:129], v[152:153] op_sel_hi:[1,0]
	v_pk_mul_f32 v[122:123], v[130:131], v[122:123]
	v_pk_mul_f32 v[120:121], v[128:129], v[120:121]
	v_exp_f32_e32 v128, v172
	v_exp_f32_e32 v129, v173
	v_pk_mul_f32 v[130:131], v[130:131], v[152:153] op_sel_hi:[1,0]
	v_pk_mul_f32 v[172:173], v[124:125], v[152:153] op_sel_hi:[1,0]
	v_exp_f32_e32 v130, v130
	v_exp_f32_e32 v131, v131
	v_pk_mul_f32 v[118:119], v[126:127], v[118:119]
	v_pk_mul_f32 v[116:117], v[124:125], v[116:117]
	v_exp_f32_e32 v124, v172
	v_exp_f32_e32 v125, v173
	v_pk_mul_f32 v[126:127], v[126:127], v[152:153] op_sel_hi:[1,0]
	v_pk_add_f32 v[128:129], v[128:129], 1.0 op_sel_hi:[1,0]
	v_exp_f32_e32 v126, v126
	v_exp_f32_e32 v127, v127
	v_pk_add_f32 v[130:131], v[130:131], 1.0 op_sel_hi:[1,0]
	v_pk_add_f32 v[124:125], v[124:125], 1.0 op_sel_hi:[1,0]
	v_rcp_f32_e32 v128, v128
	v_rcp_f32_e32 v129, v129
	v_rcp_f32_e32 v130, v130
	v_rcp_f32_e32 v131, v131
	v_rcp_f32_e32 v124, v124
	v_rcp_f32_e32 v125, v125
	v_pk_add_f32 v[126:127], v[126:127], 1.0 op_sel_hi:[1,0]
	v_or_b32_e32 v155, 16, v153
	v_rcp_f32_e32 v126, v126
	v_rcp_f32_e32 v127, v127
	v_mul_f32_e32 v154, v177, v177
	v_pk_mul_f32 v[120:121], v[120:121], v[154:155] op_sel_hi:[1,0]
	v_pk_mul_f32 v[122:123], v[122:123], v[154:155] op_sel_hi:[1,0]
	v_pk_mul_f32 v[116:117], v[116:117], v[154:155] op_sel_hi:[1,0]
	v_lshl_or_b32 v150, s64, 7, v143
	v_pk_mul_f32 v[118:119], v[118:119], v[154:155] op_sel_hi:[1,0]
	v_pk_mul_f32 v[120:121], v[120:121], v[128:129]
	v_pk_mul_f32 v[122:123], v[122:123], v[130:131]
	v_pk_mul_f32 v[116:117], v[116:117], v[124:125]
	v_ashrrev_i32_e32 v151, 31, v150
	v_pk_mul_f32 v[118:119], v[118:119], v[126:127]
	v_cvt_pk_bf16_f32 v120, v120, v121
	v_cvt_pk_bf16_f32 v121, v122, v123
	v_cvt_pk_bf16_f32 v122, v116, v117
	v_mov_b64_e32 v[116:117], s[22:23]
	v_cvt_pk_bf16_f32 v123, v118, v119
	v_mad_i64_i32 v[124:125], s[34:35], v153, s11, v[116:117]
	v_lshlrev_b64 v[118:119], 1, v[150:151]
	v_lshl_add_u64 v[124:125], v[124:125], 0, v[118:119]
	global_store_dwordx4 v[124:125], v[120:123], off sc1
	v_pk_mul_f32 v[104:105], v[112:113], v[104:105]
	v_pk_mul_f32 v[100:101], v[108:109], v[100:101]
	v_mul_f32_e32 v120, 0xbfb8aa3b, v178
	v_pk_mul_f32 v[124:125], v[112:113], v[120:121] op_sel_hi:[1,0]
	v_pk_mul_f32 v[106:107], v[114:115], v[106:107]
	v_exp_f32_e32 v112, v124
	v_exp_f32_e32 v113, v125
	v_pk_mul_f32 v[124:125], v[108:109], v[120:121] op_sel_hi:[1,0]
	v_pk_mul_f32 v[114:115], v[114:115], v[120:121] op_sel_hi:[1,0]
	v_exp_f32_e32 v108, v124
	v_exp_f32_e32 v109, v125
	v_pk_mul_f32 v[102:103], v[110:111], v[102:103]
	v_pk_mul_f32 v[110:111], v[110:111], v[120:121] op_sel_hi:[1,0]
	v_exp_f32_e32 v114, v114
	v_exp_f32_e32 v115, v115
	v_exp_f32_e32 v110, v110
	v_exp_f32_e32 v111, v111
	v_pk_add_f32 v[112:113], v[112:113], 1.0 op_sel_hi:[1,0]
	v_pk_add_f32 v[108:109], v[108:109], 1.0 op_sel_hi:[1,0]
	v_rcp_f32_e32 v112, v112
	v_rcp_f32_e32 v113, v113
	v_rcp_f32_e32 v108, v108
	v_rcp_f32_e32 v109, v109
	v_mul_f32_e32 v122, v178, v178
	v_pk_add_f32 v[114:115], v[114:115], 1.0 op_sel_hi:[1,0]
	v_pk_add_f32 v[110:111], v[110:111], 1.0 op_sel_hi:[1,0]
	v_pk_mul_f32 v[104:105], v[104:105], v[122:123] op_sel_hi:[1,0]
	v_rcp_f32_e32 v114, v114
	v_rcp_f32_e32 v115, v115
	v_rcp_f32_e32 v110, v110
	v_rcp_f32_e32 v111, v111
	v_pk_mul_f32 v[100:101], v[100:101], v[122:123] op_sel_hi:[1,0]
	v_pk_mul_f32 v[104:105], v[104:105], v[112:113]
	v_pk_mul_f32 v[108:109], v[100:101], v[108:109]
	v_cvt_pk_bf16_f32 v100, v104, v105
	v_mad_i64_i32 v[104:105], s[34:35], v155, s11, v[116:117]
	v_pk_mul_f32 v[106:107], v[106:107], v[122:123] op_sel_hi:[1,0]
	v_pk_mul_f32 v[102:103], v[102:103], v[122:123] op_sel_hi:[1,0]
	v_lshl_add_u64 v[104:105], v[104:105], 0, v[118:119]
	v_pk_mul_f32 v[106:107], v[106:107], v[114:115]
	v_pk_mul_f32 v[110:111], v[102:103], v[110:111]
	v_cvt_pk_bf16_f32 v101, v106, v107
	v_cvt_pk_bf16_f32 v102, v108, v109
	v_pk_mul_f32 v[88:89], v[96:97], v[88:89]
	v_cvt_pk_bf16_f32 v103, v110, v111
	global_store_dwordx4 v[104:105], v[100:103], off sc1
	v_pk_mul_f32 v[84:85], v[92:93], v[84:85]
	v_pk_mul_f32 v[90:91], v[98:99], v[90:91]
	v_mul_f32_e32 v100, 0xbfb8aa3b, v179
	v_pk_mul_f32 v[104:105], v[96:97], v[100:101] op_sel_hi:[1,0]
	v_pk_mul_f32 v[98:99], v[98:99], v[100:101] op_sel_hi:[1,0]
	v_exp_f32_e32 v96, v104
	v_exp_f32_e32 v97, v105
	v_pk_mul_f32 v[104:105], v[92:93], v[100:101] op_sel_hi:[1,0]
	v_pk_mul_f32 v[86:87], v[94:95], v[86:87]
	v_exp_f32_e32 v92, v104
	v_exp_f32_e32 v93, v105
	v_pk_mul_f32 v[94:95], v[94:95], v[100:101] op_sel_hi:[1,0]
	v_exp_f32_e32 v98, v98
	v_exp_f32_e32 v99, v99
	v_exp_f32_e32 v94, v94
	v_exp_f32_e32 v95, v95
	v_pk_add_f32 v[96:97], v[96:97], 1.0 op_sel_hi:[1,0]
	v_pk_add_f32 v[92:93], v[92:93], 1.0 op_sel_hi:[1,0]
	v_rcp_f32_e32 v96, v96
	v_rcp_f32_e32 v97, v97
	v_rcp_f32_e32 v92, v92
	v_rcp_f32_e32 v93, v93
	v_mul_f32_e32 v102, v179, v179
	v_pk_add_f32 v[98:99], v[98:99], 1.0 op_sel_hi:[1,0]
	v_pk_add_f32 v[94:95], v[94:95], 1.0 op_sel_hi:[1,0]
	v_pk_mul_f32 v[88:89], v[88:89], v[102:103] op_sel_hi:[1,0]
	v_rcp_f32_e32 v98, v98
	v_rcp_f32_e32 v99, v99
	v_rcp_f32_e32 v94, v94
	v_rcp_f32_e32 v95, v95
	v_or_b32_e32 v174, 32, v153
	v_pk_mul_f32 v[84:85], v[84:85], v[102:103] op_sel_hi:[1,0]
	v_pk_mul_f32 v[88:89], v[88:89], v[96:97]
	v_pk_mul_f32 v[92:93], v[84:85], v[92:93]
	v_cvt_pk_bf16_f32 v84, v88, v89
	v_mad_i64_i32 v[88:89], s[34:35], v174, s11, v[116:117]
	v_pk_mul_f32 v[90:91], v[90:91], v[102:103] op_sel_hi:[1,0]
	v_pk_mul_f32 v[86:87], v[86:87], v[102:103] op_sel_hi:[1,0]
	v_lshl_add_u64 v[88:89], v[88:89], 0, v[118:119]
	v_pk_mul_f32 v[90:91], v[90:91], v[98:99]
	v_pk_mul_f32 v[94:95], v[86:87], v[94:95]
	v_cvt_pk_bf16_f32 v85, v90, v91
	v_cvt_pk_bf16_f32 v86, v92, v93
	v_pk_mul_f32 v[72:73], v[80:81], v[72:73]
	v_cvt_pk_bf16_f32 v87, v94, v95
	global_store_dwordx4 v[88:89], v[84:87], off sc1
	v_pk_mul_f32 v[68:69], v[76:77], v[68:69]
	v_pk_mul_f32 v[74:75], v[82:83], v[74:75]
	v_mul_f32_e32 v84, 0xbfb8aa3b, v180
	v_pk_mul_f32 v[88:89], v[80:81], v[84:85] op_sel_hi:[1,0]
	v_pk_mul_f32 v[82:83], v[82:83], v[84:85] op_sel_hi:[1,0]
	v_exp_f32_e32 v80, v88
	v_exp_f32_e32 v81, v89
	v_pk_mul_f32 v[88:89], v[76:77], v[84:85] op_sel_hi:[1,0]
	v_pk_mul_f32 v[70:71], v[78:79], v[70:71]
	v_exp_f32_e32 v76, v88
	v_exp_f32_e32 v77, v89
	v_pk_mul_f32 v[78:79], v[78:79], v[84:85] op_sel_hi:[1,0]
	v_exp_f32_e32 v82, v82
	v_exp_f32_e32 v83, v83
	v_exp_f32_e32 v78, v78
	v_exp_f32_e32 v79, v79
	v_pk_add_f32 v[80:81], v[80:81], 1.0 op_sel_hi:[1,0]
	v_pk_add_f32 v[76:77], v[76:77], 1.0 op_sel_hi:[1,0]
	v_rcp_f32_e32 v80, v80
	v_rcp_f32_e32 v81, v81
	v_rcp_f32_e32 v76, v76
	v_rcp_f32_e32 v77, v77
	v_mul_f32_e32 v86, v180, v180
	v_pk_add_f32 v[82:83], v[82:83], 1.0 op_sel_hi:[1,0]
	v_pk_add_f32 v[78:79], v[78:79], 1.0 op_sel_hi:[1,0]
	v_pk_mul_f32 v[72:73], v[72:73], v[86:87] op_sel_hi:[1,0]
	v_rcp_f32_e32 v82, v82
	v_rcp_f32_e32 v83, v83
	v_rcp_f32_e32 v78, v78
	v_rcp_f32_e32 v79, v79
	v_or_b32_e32 v175, 48, v153
	v_pk_mul_f32 v[68:69], v[68:69], v[86:87] op_sel_hi:[1,0]
	v_pk_mul_f32 v[72:73], v[72:73], v[80:81]
	v_pk_mul_f32 v[76:77], v[68:69], v[76:77]
	v_cvt_pk_bf16_f32 v68, v72, v73
	v_mad_i64_i32 v[72:73], s[34:35], v175, s11, v[116:117]
	v_pk_mul_f32 v[74:75], v[74:75], v[86:87] op_sel_hi:[1,0]
	v_pk_mul_f32 v[70:71], v[70:71], v[86:87] op_sel_hi:[1,0]
	v_lshl_add_u64 v[72:73], v[72:73], 0, v[118:119]
	v_pk_mul_f32 v[74:75], v[74:75], v[82:83]
	v_pk_mul_f32 v[78:79], v[70:71], v[78:79]
	v_cvt_pk_bf16_f32 v69, v74, v75
	v_cvt_pk_bf16_f32 v70, v76, v77
	v_pk_mul_f32 v[56:57], v[64:65], v[56:57]
	v_cvt_pk_bf16_f32 v71, v78, v79
	global_store_dwordx4 v[72:73], v[68:71], off sc1
	v_pk_mul_f32 v[52:53], v[60:61], v[52:53]
	v_pk_mul_f32 v[58:59], v[66:67], v[58:59]
	v_mul_f32_e32 v68, 0xbfb8aa3b, v181
	v_pk_mul_f32 v[72:73], v[64:65], v[68:69] op_sel_hi:[1,0]
	v_pk_mul_f32 v[66:67], v[66:67], v[68:69] op_sel_hi:[1,0]
	v_exp_f32_e32 v64, v72
	v_exp_f32_e32 v65, v73
	v_pk_mul_f32 v[72:73], v[60:61], v[68:69] op_sel_hi:[1,0]
	v_pk_mul_f32 v[54:55], v[62:63], v[54:55]
	v_exp_f32_e32 v60, v72
	v_exp_f32_e32 v61, v73
	v_pk_mul_f32 v[62:63], v[62:63], v[68:69] op_sel_hi:[1,0]
	v_exp_f32_e32 v66, v66
	v_exp_f32_e32 v67, v67
	v_exp_f32_e32 v62, v62
	v_exp_f32_e32 v63, v63
	v_pk_add_f32 v[64:65], v[64:65], 1.0 op_sel_hi:[1,0]
	v_pk_add_f32 v[60:61], v[60:61], 1.0 op_sel_hi:[1,0]
	v_rcp_f32_e32 v64, v64
	v_rcp_f32_e32 v65, v65
	v_rcp_f32_e32 v60, v60
	v_rcp_f32_e32 v61, v61
	v_mul_f32_e32 v70, v181, v181
	v_pk_add_f32 v[66:67], v[66:67], 1.0 op_sel_hi:[1,0]
	v_pk_add_f32 v[62:63], v[62:63], 1.0 op_sel_hi:[1,0]
	v_pk_mul_f32 v[56:57], v[56:57], v[70:71] op_sel_hi:[1,0]
	v_rcp_f32_e32 v66, v66
	v_rcp_f32_e32 v67, v67
	v_rcp_f32_e32 v62, v62
	v_rcp_f32_e32 v63, v63
	v_pk_mul_f32 v[52:53], v[52:53], v[70:71] op_sel_hi:[1,0]
	v_pk_mul_f32 v[56:57], v[56:57], v[64:65]
	v_pk_mul_f32 v[60:61], v[52:53], v[60:61]
	v_cvt_pk_bf16_f32 v52, v56, v57
	v_mad_i64_i32 v[56:57], s[34:35], v176, s11, v[116:117]
	v_pk_mul_f32 v[58:59], v[58:59], v[70:71] op_sel_hi:[1,0]
	v_pk_mul_f32 v[54:55], v[54:55], v[70:71] op_sel_hi:[1,0]
	v_lshl_add_u64 v[56:57], v[56:57], 0, v[118:119]
	v_pk_mul_f32 v[58:59], v[58:59], v[66:67]
	v_pk_mul_f32 v[62:63], v[54:55], v[62:63]
	v_cvt_pk_bf16_f32 v53, v58, v59
	v_cvt_pk_bf16_f32 v54, v60, v61
	v_pk_mul_f32 v[40:41], v[48:49], v[40:41]
	v_cvt_pk_bf16_f32 v55, v62, v63
	global_store_dwordx4 v[56:57], v[52:55], off sc1
	v_pk_mul_f32 v[36:37], v[44:45], v[36:37]
	v_pk_mul_f32 v[42:43], v[50:51], v[42:43]
	v_mul_f32_e32 v52, 0xbfb8aa3b, v182
	v_pk_mul_f32 v[56:57], v[48:49], v[52:53] op_sel_hi:[1,0]
	v_pk_mul_f32 v[50:51], v[50:51], v[52:53] op_sel_hi:[1,0]
	v_exp_f32_e32 v48, v56
	v_exp_f32_e32 v49, v57
	v_pk_mul_f32 v[56:57], v[44:45], v[52:53] op_sel_hi:[1,0]
	v_pk_mul_f32 v[38:39], v[46:47], v[38:39]
	v_exp_f32_e32 v44, v56
	v_exp_f32_e32 v45, v57
	v_pk_mul_f32 v[46:47], v[46:47], v[52:53] op_sel_hi:[1,0]
	v_exp_f32_e32 v50, v50
	v_exp_f32_e32 v51, v51
	v_exp_f32_e32 v46, v46
	v_exp_f32_e32 v47, v47
	v_pk_add_f32 v[48:49], v[48:49], 1.0 op_sel_hi:[1,0]
	v_pk_add_f32 v[44:45], v[44:45], 1.0 op_sel_hi:[1,0]
	v_rcp_f32_e32 v48, v48
	v_rcp_f32_e32 v49, v49
	v_rcp_f32_e32 v44, v44
	v_rcp_f32_e32 v45, v45
	v_mul_f32_e32 v54, v182, v182
	v_pk_add_f32 v[50:51], v[50:51], 1.0 op_sel_hi:[1,0]
	v_pk_add_f32 v[46:47], v[46:47], 1.0 op_sel_hi:[1,0]
	v_pk_mul_f32 v[40:41], v[40:41], v[54:55] op_sel_hi:[1,0]
	v_rcp_f32_e32 v50, v50
	v_rcp_f32_e32 v51, v51
	v_rcp_f32_e32 v46, v46
	v_rcp_f32_e32 v47, v47
	v_pk_mul_f32 v[36:37], v[36:37], v[54:55] op_sel_hi:[1,0]
	v_pk_mul_f32 v[40:41], v[40:41], v[48:49]
	v_pk_mul_f32 v[44:45], v[36:37], v[44:45]
	v_cvt_pk_bf16_f32 v36, v40, v41
	v_mad_i64_i32 v[40:41], s[34:35], v148, s11, v[116:117]
	v_pk_mul_f32 v[42:43], v[42:43], v[54:55] op_sel_hi:[1,0]
	v_pk_mul_f32 v[38:39], v[38:39], v[54:55] op_sel_hi:[1,0]
	v_lshl_add_u64 v[40:41], v[40:41], 0, v[118:119]
	v_pk_mul_f32 v[42:43], v[42:43], v[50:51]
	v_pk_mul_f32 v[46:47], v[38:39], v[46:47]
	v_cvt_pk_bf16_f32 v37, v42, v43
	v_cvt_pk_bf16_f32 v38, v44, v45
	v_pk_mul_f32 v[24:25], v[32:33], v[24:25]
	v_cvt_pk_bf16_f32 v39, v46, v47
	global_store_dwordx4 v[40:41], v[36:39], off sc1
	v_pk_mul_f32 v[20:21], v[28:29], v[20:21]
	v_pk_mul_f32 v[26:27], v[34:35], v[26:27]
	v_mul_f32_e32 v36, 0xbfb8aa3b, v149
	v_pk_mul_f32 v[40:41], v[32:33], v[36:37] op_sel_hi:[1,0]
	v_pk_mul_f32 v[34:35], v[34:35], v[36:37] op_sel_hi:[1,0]
	v_exp_f32_e32 v32, v40
	v_exp_f32_e32 v33, v41
	v_pk_mul_f32 v[40:41], v[28:29], v[36:37] op_sel_hi:[1,0]
	v_pk_mul_f32 v[22:23], v[30:31], v[22:23]
	v_exp_f32_e32 v28, v40
	v_exp_f32_e32 v29, v41
	v_pk_mul_f32 v[30:31], v[30:31], v[36:37] op_sel_hi:[1,0]
	v_exp_f32_e32 v34, v34
	v_exp_f32_e32 v35, v35
	v_exp_f32_e32 v30, v30
	v_exp_f32_e32 v31, v31
	v_pk_add_f32 v[32:33], v[32:33], 1.0 op_sel_hi:[1,0]
	v_pk_add_f32 v[28:29], v[28:29], 1.0 op_sel_hi:[1,0]
	v_rcp_f32_e32 v32, v32
	v_rcp_f32_e32 v33, v33
	v_rcp_f32_e32 v28, v28
	v_rcp_f32_e32 v29, v29
	v_mul_f32_e32 v38, v149, v149
	v_pk_add_f32 v[34:35], v[34:35], 1.0 op_sel_hi:[1,0]
	v_pk_add_f32 v[30:31], v[30:31], 1.0 op_sel_hi:[1,0]
	v_pk_mul_f32 v[24:25], v[24:25], v[38:39] op_sel_hi:[1,0]
	v_rcp_f32_e32 v34, v34
	v_rcp_f32_e32 v35, v35
	v_rcp_f32_e32 v30, v30
	v_rcp_f32_e32 v31, v31
	v_pk_mul_f32 v[20:21], v[20:21], v[38:39] op_sel_hi:[1,0]
	v_pk_mul_f32 v[24:25], v[24:25], v[32:33]
	v_pk_mul_f32 v[28:29], v[20:21], v[28:29]
	v_cvt_pk_bf16_f32 v20, v24, v25
	v_mad_i64_i32 v[24:25], s[34:35], v146, s11, v[116:117]
	v_pk_mul_f32 v[26:27], v[26:27], v[38:39] op_sel_hi:[1,0]
	v_pk_mul_f32 v[22:23], v[22:23], v[38:39] op_sel_hi:[1,0]
	v_lshl_add_u64 v[24:25], v[24:25], 0, v[118:119]
	v_pk_mul_f32 v[26:27], v[26:27], v[34:35]
	v_pk_mul_f32 v[30:31], v[22:23], v[30:31]
	v_cvt_pk_bf16_f32 v21, v26, v27
	v_cvt_pk_bf16_f32 v22, v28, v29
	v_pk_mul_f32 v[8:9], v[16:17], v[8:9]
	v_cvt_pk_bf16_f32 v23, v30, v31
	global_store_dwordx4 v[24:25], v[20:23], off sc1
	v_pk_mul_f32 v[4:5], v[12:13], v[4:5]
	v_pk_mul_f32 v[10:11], v[18:19], v[10:11]
	v_mul_f32_e32 v20, 0xbfb8aa3b, v147
	v_pk_mul_f32 v[24:25], v[16:17], v[20:21] op_sel_hi:[1,0]
	v_pk_mul_f32 v[18:19], v[18:19], v[20:21] op_sel_hi:[1,0]
	v_exp_f32_e32 v16, v24
	v_exp_f32_e32 v17, v25
	v_pk_mul_f32 v[24:25], v[12:13], v[20:21] op_sel_hi:[1,0]
	v_pk_mul_f32 v[6:7], v[14:15], v[6:7]
	v_exp_f32_e32 v12, v24
	v_exp_f32_e32 v13, v25
	v_pk_mul_f32 v[14:15], v[14:15], v[20:21] op_sel_hi:[1,0]
	v_exp_f32_e32 v18, v18
	v_exp_f32_e32 v19, v19
	v_exp_f32_e32 v14, v14
	v_exp_f32_e32 v15, v15
	v_pk_add_f32 v[16:17], v[16:17], 1.0 op_sel_hi:[1,0]
	v_pk_add_f32 v[12:13], v[12:13], 1.0 op_sel_hi:[1,0]
	v_rcp_f32_e32 v16, v16
	v_rcp_f32_e32 v17, v17
	v_rcp_f32_e32 v12, v12
	v_rcp_f32_e32 v13, v13
	v_mul_f32_e32 v22, v147, v147
	v_pk_add_f32 v[18:19], v[18:19], 1.0 op_sel_hi:[1,0]
	v_pk_add_f32 v[14:15], v[14:15], 1.0 op_sel_hi:[1,0]
	v_pk_mul_f32 v[8:9], v[8:9], v[22:23] op_sel_hi:[1,0]
	v_rcp_f32_e32 v18, v18
	v_rcp_f32_e32 v19, v19
	v_rcp_f32_e32 v14, v14
	v_rcp_f32_e32 v15, v15
	v_pk_mul_f32 v[4:5], v[4:5], v[22:23] op_sel_hi:[1,0]
	v_pk_mul_f32 v[8:9], v[8:9], v[16:17]
	v_pk_mul_f32 v[12:13], v[4:5], v[12:13]
	v_cvt_pk_bf16_f32 v4, v8, v9
	v_mad_i64_i32 v[8:9], s[34:35], v145, s11, v[116:117]
	v_pk_mul_f32 v[10:11], v[10:11], v[22:23] op_sel_hi:[1,0]
	v_pk_mul_f32 v[6:7], v[6:7], v[22:23] op_sel_hi:[1,0]
	v_lshl_add_u64 v[8:9], v[8:9], 0, v[118:119]
	s_andn2_b64 vcc, exec, s[38:39]
	s_mov_b64 s[34:35], -1
	v_pk_mul_f32 v[10:11], v[10:11], v[18:19]
	v_pk_mul_f32 v[14:15], v[6:7], v[14:15]
	v_cvt_pk_bf16_f32 v5, v10, v11
	v_cvt_pk_bf16_f32 v6, v12, v13
	s_nop 0
	v_cvt_pk_bf16_f32 v7, v14, v15
	global_store_dwordx4 v[8:9], v[4:7], off sc1
	s_cbranch_vccnz .LBB0_165
	s_andn2_b64 vcc, exec, s[26:27]
	s_cbranch_vccnz .LBB0_164
	s_barrier
	s_branch .LBB0_164

.LBB0_255:
	v_cvt_pk_bf16_f32 v144, v144, v145
	v_cvt_pk_bf16_f32 v145, v146, v147
	v_cvt_pk_bf16_f32 v146, v140, v141
	v_lshl_add_u64 v[140:141], v[176:177], 1, v[202:203]
	s_mov_b64 s[36:37], 0
	v_cvt_pk_bf16_f32 v147, v142, v143
	global_store_dwordx4 v[140:141], v[144:147], off sc1
	v_cvt_pk_bf16_f32 v136, v136, v137
	v_cvt_pk_bf16_f32 v137, v138, v139
	v_cvt_pk_bf16_f32 v138, v132, v133
	v_cvt_pk_bf16_f32 v139, v134, v135
	global_store_dwordx4 v[140:141], v[136:139], off offset:256 sc1
.LBB0_256:
	s_lshl_b32 s55, s64, 7
	s_and_b64 vcc, exec, s[36:37]
	v_lshlrev_b32_e32 v132, 1, v154
	s_cbranch_vccz .LBB0_258
	v_mul_f32_e32 v116, 0xbfb8aa3b, v116
	v_mul_f32_e32 v121, 0xbfb8aa3b, v121
	v_exp_f32_e32 v116, v116
	v_exp_f32_e32 v121, v121
	v_mul_f32_e32 v117, 0xbfb8aa3b, v117
	v_exp_f32_e32 v117, v117
	v_add_f32_e32 v116, 1.0, v116
	v_add_f32_e32 v121, 1.0, v121
	v_rcp_f32_e32 v116, v116
	v_rcp_f32_e32 v121, v121
	v_add_f32_e32 v117, 1.0, v117
	v_rcp_f32_e32 v117, v117
	v_mul_f32_e32 v124, v124, v116
	v_mul_f32_e32 v116, v129, v121
	v_mul_f32_e32 v121, 0xbfb8aa3b, v122
	v_exp_f32_e32 v121, v121
	v_mul_f32_e32 v120, 0xbfb8aa3b, v120
	v_exp_f32_e32 v120, v120
	v_mul_f32_e32 v118, 0xbfb8aa3b, v118
	v_mul_f32_e32 v122, v125, v117
	v_add_f32_e32 v117, 1.0, v121
	v_mul_f32_e32 v121, 0xbfb8aa3b, v123
	v_exp_f32_e32 v118, v118
	v_exp_f32_e32 v121, v121
	v_mul_f32_e32 v119, 0xbfb8aa3b, v119
	v_exp_f32_e32 v119, v119
	v_add_f32_e32 v120, 1.0, v120
	v_rcp_f32_e32 v120, v120
	v_add_f32_e32 v118, 1.0, v118
	v_add_f32_e32 v121, 1.0, v121
	v_rcp_f32_e32 v118, v118
	v_rcp_f32_e32 v121, v121
	v_add_f32_e32 v119, 1.0, v119
	v_rcp_f32_e32 v117, v117
	v_rcp_f32_e32 v119, v119
	v_mul_f32_e32 v120, v128, v120
	s_lshl_b32 s64, s55, 1
	v_mul_f32_e32 v123, v126, v118
	v_mul_f32_e32 v118, v131, v121
	v_cvt_pk_bf16_f32 v116, v120, v116
	v_lshl_add_u64 v[120:121], v[202:203], 0, s[64:65]
	v_mov_b32_e32 v133, v2
	v_mul_f32_e32 v117, v130, v117
	v_mul_f32_e32 v119, v127, v119
	v_lshl_add_u64 v[120:121], v[120:121], 0, v[132:133]
	v_cvt_pk_bf16_f32 v117, v117, v118
	v_cvt_pk_bf16_f32 v118, v124, v122
	v_cvt_pk_bf16_f32 v119, v123, v119
	global_store_dwordx4 v[120:121], v[116:119], off offset:1536 sc1

.LBB0_267:
	v_cvt_pk_bf16_f32 v128, v128, v129
	v_cvt_pk_bf16_f32 v129, v130, v131
	v_cvt_pk_bf16_f32 v130, v124, v125
	v_lshl_add_u64 v[124:125], v[176:177], 1, v[134:135]
	s_mov_b64 s[34:35], 0
	v_cvt_pk_bf16_f32 v131, v126, v127
	global_store_dwordx4 v[124:125], v[128:131], off sc1
	v_cvt_pk_bf16_f32 v120, v120, v121
	v_cvt_pk_bf16_f32 v121, v122, v123
	v_cvt_pk_bf16_f32 v122, v116, v117
	v_cvt_pk_bf16_f32 v123, v118, v119
	global_store_dwordx4 v[124:125], v[120:123], off offset:256 sc1
.LBB0_268:
	s_and_b64 vcc, exec, s[34:35]
	s_cbranch_vccz .LBB0_270
	v_mul_f32_e32 v100, 0xbfb8aa3b, v100
	v_mul_f32_e32 v105, 0xbfb8aa3b, v105
	v_exp_f32_e32 v100, v100
	v_exp_f32_e32 v105, v105
	v_mul_f32_e32 v101, 0xbfb8aa3b, v101
	v_exp_f32_e32 v101, v101
	v_add_f32_e32 v100, 1.0, v100
	v_add_f32_e32 v105, 1.0, v105
	v_rcp_f32_e32 v100, v100
	v_rcp_f32_e32 v105, v105
	v_add_f32_e32 v101, 1.0, v101
	v_rcp_f32_e32 v101, v101
	v_mul_f32_e32 v108, v108, v100
	v_mul_f32_e32 v100, v113, v105
	v_mul_f32_e32 v105, 0xbfb8aa3b, v106
	v_exp_f32_e32 v105, v105
	v_mul_f32_e32 v104, 0xbfb8aa3b, v104
	v_exp_f32_e32 v104, v104
	v_mul_f32_e32 v102, 0xbfb8aa3b, v102
	v_mul_f32_e32 v106, v109, v101
	v_add_f32_e32 v101, 1.0, v105
	v_mul_f32_e32 v105, 0xbfb8aa3b, v107
	v_exp_f32_e32 v102, v102
	v_exp_f32_e32 v105, v105
	v_mul_f32_e32 v103, 0xbfb8aa3b, v103
	v_exp_f32_e32 v103, v103
	v_add_f32_e32 v104, 1.0, v104
	v_rcp_f32_e32 v104, v104
	v_add_f32_e32 v102, 1.0, v102
	v_add_f32_e32 v105, 1.0, v105
	v_rcp_f32_e32 v102, v102
	v_rcp_f32_e32 v105, v105
	v_add_f32_e32 v103, 1.0, v103
	v_rcp_f32_e32 v101, v101
	v_rcp_f32_e32 v103, v103
	v_mul_f32_e32 v104, v112, v104
	s_lshl_b32 s64, s55, 1
	v_mul_f32_e32 v107, v110, v102
	v_mul_f32_e32 v102, v115, v105
	v_cvt_pk_bf16_f32 v100, v104, v100
	v_lshl_add_u64 v[104:105], v[134:135], 0, s[64:65]
	v_mov_b32_e32 v133, v2
	v_mul_f32_e32 v101, v114, v101
	v_mul_f32_e32 v103, v111, v103
	v_lshl_add_u64 v[104:105], v[104:105], 0, v[132:133]
	v_cvt_pk_bf16_f32 v101, v101, v102
	v_cvt_pk_bf16_f32 v102, v108, v106
	v_cvt_pk_bf16_f32 v103, v107, v103
	global_store_dwordx4 v[104:105], v[100:103], off offset:1536 sc1

.LBB0_279:
	v_cvt_pk_bf16_f32 v112, v112, v113
	v_cvt_pk_bf16_f32 v113, v114, v115
	v_cvt_pk_bf16_f32 v114, v108, v109
	v_lshl_add_u64 v[108:109], v[176:177], 1, v[116:117]
	s_mov_b64 s[34:35], 0
	v_cvt_pk_bf16_f32 v115, v110, v111
	global_store_dwordx4 v[108:109], v[112:115], off sc1
	v_cvt_pk_bf16_f32 v104, v104, v105
	v_cvt_pk_bf16_f32 v105, v106, v107
	v_cvt_pk_bf16_f32 v106, v100, v101
	v_cvt_pk_bf16_f32 v107, v102, v103
	global_store_dwordx4 v[108:109], v[104:107], off offset:256 sc1
.LBB0_280:
	s_and_b64 vcc, exec, s[34:35]
	s_cbranch_vccz .LBB0_282
	v_mul_f32_e32 v84, 0xbfb8aa3b, v84
	v_mul_f32_e32 v89, 0xbfb8aa3b, v89
	v_exp_f32_e32 v84, v84
	v_exp_f32_e32 v89, v89
	v_mul_f32_e32 v85, 0xbfb8aa3b, v85
	v_exp_f32_e32 v85, v85
	v_add_f32_e32 v84, 1.0, v84
	v_add_f32_e32 v89, 1.0, v89
	v_rcp_f32_e32 v84, v84
	v_rcp_f32_e32 v89, v89
	v_add_f32_e32 v85, 1.0, v85
	v_rcp_f32_e32 v85, v85
	v_mul_f32_e32 v92, v92, v84
	v_mul_f32_e32 v84, v97, v89
	v_mul_f32_e32 v89, 0xbfb8aa3b, v90
	v_exp_f32_e32 v89, v89
	v_mul_f32_e32 v88, 0xbfb8aa3b, v88
	v_exp_f32_e32 v88, v88
	v_mul_f32_e32 v86, 0xbfb8aa3b, v86
	v_mul_f32_e32 v90, v93, v85
	v_add_f32_e32 v85, 1.0, v89
	v_mul_f32_e32 v89, 0xbfb8aa3b, v91
	v_exp_f32_e32 v86, v86
	v_exp_f32_e32 v89, v89
	v_mul_f32_e32 v87, 0xbfb8aa3b, v87
	v_exp_f32_e32 v87, v87
	v_add_f32_e32 v88, 1.0, v88
	v_rcp_f32_e32 v88, v88
	v_add_f32_e32 v86, 1.0, v86
	v_add_f32_e32 v89, 1.0, v89
	v_rcp_f32_e32 v86, v86
	v_rcp_f32_e32 v89, v89
	v_add_f32_e32 v87, 1.0, v87
	v_rcp_f32_e32 v85, v85
	v_rcp_f32_e32 v87, v87
	v_mul_f32_e32 v88, v96, v88
	s_lshl_b32 s64, s55, 1
	v_mul_f32_e32 v91, v94, v86
	v_mul_f32_e32 v86, v99, v89
	v_cvt_pk_bf16_f32 v84, v88, v84
	v_lshl_add_u64 v[88:89], v[116:117], 0, s[64:65]
	v_mov_b32_e32 v133, v2
	v_mul_f32_e32 v85, v98, v85
	v_mul_f32_e32 v87, v95, v87
	v_lshl_add_u64 v[88:89], v[88:89], 0, v[132:133]
	v_cvt_pk_bf16_f32 v85, v85, v86
	v_cvt_pk_bf16_f32 v86, v92, v90
	v_cvt_pk_bf16_f32 v87, v91, v87
	global_store_dwordx4 v[88:89], v[84:87], off offset:1536 sc1

.LBB0_291:
	v_cvt_pk_bf16_f32 v96, v96, v97
	v_cvt_pk_bf16_f32 v97, v98, v99
	v_cvt_pk_bf16_f32 v98, v92, v93
	v_lshl_add_u64 v[92:93], v[176:177], 1, v[100:101]
	s_mov_b64 s[34:35], 0
	v_cvt_pk_bf16_f32 v99, v94, v95
	global_store_dwordx4 v[92:93], v[96:99], off sc1
	v_cvt_pk_bf16_f32 v88, v88, v89
	v_cvt_pk_bf16_f32 v89, v90, v91
	v_cvt_pk_bf16_f32 v90, v84, v85
	v_cvt_pk_bf16_f32 v91, v86, v87
	global_store_dwordx4 v[92:93], v[88:91], off offset:256 sc1
.LBB0_292:
	s_and_b64 vcc, exec, s[34:35]
	s_cbranch_vccz .LBB0_294
	v_mul_f32_e32 v68, 0xbfb8aa3b, v68
	v_mul_f32_e32 v73, 0xbfb8aa3b, v73
	v_exp_f32_e32 v68, v68
	v_exp_f32_e32 v73, v73
	v_mul_f32_e32 v69, 0xbfb8aa3b, v69
	v_exp_f32_e32 v69, v69
	v_add_f32_e32 v68, 1.0, v68
	v_add_f32_e32 v73, 1.0, v73
	v_rcp_f32_e32 v68, v68
	v_rcp_f32_e32 v73, v73
	v_add_f32_e32 v69, 1.0, v69
	v_rcp_f32_e32 v69, v69
	v_mul_f32_e32 v76, v76, v68
	v_mul_f32_e32 v68, v81, v73
	v_mul_f32_e32 v73, 0xbfb8aa3b, v74
	v_exp_f32_e32 v73, v73
	v_mul_f32_e32 v72, 0xbfb8aa3b, v72
	v_exp_f32_e32 v72, v72
	v_mul_f32_e32 v70, 0xbfb8aa3b, v70
	v_mul_f32_e32 v74, v77, v69
	v_add_f32_e32 v69, 1.0, v73
	v_mul_f32_e32 v73, 0xbfb8aa3b, v75
	v_exp_f32_e32 v70, v70
	v_exp_f32_e32 v73, v73
	v_mul_f32_e32 v71, 0xbfb8aa3b, v71
	v_exp_f32_e32 v71, v71
	v_add_f32_e32 v72, 1.0, v72
	v_rcp_f32_e32 v72, v72
	v_add_f32_e32 v70, 1.0, v70
	v_add_f32_e32 v73, 1.0, v73
	v_rcp_f32_e32 v70, v70
	v_rcp_f32_e32 v73, v73
	v_add_f32_e32 v71, 1.0, v71
	v_rcp_f32_e32 v69, v69
	v_rcp_f32_e32 v71, v71
	v_mul_f32_e32 v72, v80, v72
	s_lshl_b32 s64, s55, 1
	v_mul_f32_e32 v75, v78, v70
	v_mul_f32_e32 v70, v83, v73
	v_cvt_pk_bf16_f32 v68, v72, v68
	v_lshl_add_u64 v[72:73], v[100:101], 0, s[64:65]
	v_mov_b32_e32 v133, v2
	v_mul_f32_e32 v69, v82, v69
	v_mul_f32_e32 v71, v79, v71
	v_lshl_add_u64 v[72:73], v[72:73], 0, v[132:133]
	v_cvt_pk_bf16_f32 v69, v69, v70
	v_cvt_pk_bf16_f32 v70, v76, v74
	v_cvt_pk_bf16_f32 v71, v75, v71
	global_store_dwordx4 v[72:73], v[68:71], off offset:1536 sc1

.LBB0_303:
	v_cvt_pk_bf16_f32 v80, v80, v81
	v_cvt_pk_bf16_f32 v81, v82, v83
	v_cvt_pk_bf16_f32 v82, v76, v77
	v_lshl_add_u64 v[76:77], v[176:177], 1, v[84:85]
	s_mov_b64 s[34:35], 0
	v_cvt_pk_bf16_f32 v83, v78, v79
	global_store_dwordx4 v[76:77], v[80:83], off sc1
	v_cvt_pk_bf16_f32 v72, v72, v73
	v_cvt_pk_bf16_f32 v73, v74, v75
	v_cvt_pk_bf16_f32 v74, v68, v69
	v_cvt_pk_bf16_f32 v75, v70, v71
	global_store_dwordx4 v[76:77], v[72:75], off offset:256 sc1
.LBB0_304:
	s_and_b64 vcc, exec, s[34:35]
	s_cbranch_vccz .LBB0_306
	v_mul_f32_e32 v52, 0xbfb8aa3b, v52
	v_mul_f32_e32 v57, 0xbfb8aa3b, v57
	v_exp_f32_e32 v52, v52
	v_exp_f32_e32 v57, v57
	v_mul_f32_e32 v53, 0xbfb8aa3b, v53
	v_exp_f32_e32 v53, v53
	v_add_f32_e32 v52, 1.0, v52
	v_add_f32_e32 v57, 1.0, v57
	v_rcp_f32_e32 v52, v52
	v_rcp_f32_e32 v57, v57
	v_add_f32_e32 v53, 1.0, v53
	v_rcp_f32_e32 v53, v53
	v_mul_f32_e32 v60, v60, v52
	v_mul_f32_e32 v52, v65, v57
	v_mul_f32_e32 v57, 0xbfb8aa3b, v58
	v_exp_f32_e32 v57, v57
	v_mul_f32_e32 v56, 0xbfb8aa3b, v56
	v_exp_f32_e32 v56, v56
	v_mul_f32_e32 v54, 0xbfb8aa3b, v54
	v_mul_f32_e32 v58, v61, v53
	v_add_f32_e32 v53, 1.0, v57
	v_mul_f32_e32 v57, 0xbfb8aa3b, v59
	v_exp_f32_e32 v54, v54
	v_exp_f32_e32 v57, v57
	v_mul_f32_e32 v55, 0xbfb8aa3b, v55
	v_exp_f32_e32 v55, v55
	v_add_f32_e32 v56, 1.0, v56
	v_rcp_f32_e32 v56, v56
	v_add_f32_e32 v54, 1.0, v54
	v_add_f32_e32 v57, 1.0, v57
	v_rcp_f32_e32 v54, v54
	v_rcp_f32_e32 v57, v57
	v_add_f32_e32 v55, 1.0, v55
	v_rcp_f32_e32 v53, v53
	v_rcp_f32_e32 v55, v55
	v_mul_f32_e32 v56, v64, v56
	s_lshl_b32 s64, s55, 1
	v_mul_f32_e32 v59, v62, v54
	v_mul_f32_e32 v54, v67, v57
	v_cvt_pk_bf16_f32 v52, v56, v52
	v_lshl_add_u64 v[56:57], v[84:85], 0, s[64:65]
	v_mov_b32_e32 v133, v2
	v_mul_f32_e32 v53, v66, v53
	v_mul_f32_e32 v55, v63, v55
	v_lshl_add_u64 v[56:57], v[56:57], 0, v[132:133]
	v_cvt_pk_bf16_f32 v53, v53, v54
	v_cvt_pk_bf16_f32 v54, v60, v58
	v_cvt_pk_bf16_f32 v55, v59, v55
	global_store_dwordx4 v[56:57], v[52:55], off offset:1536 sc1

.LBB0_315:
	v_cvt_pk_bf16_f32 v64, v64, v65
	v_cvt_pk_bf16_f32 v65, v66, v67
	v_cvt_pk_bf16_f32 v66, v60, v61
	v_lshl_add_u64 v[60:61], v[176:177], 1, v[68:69]
	s_mov_b64 s[34:35], 0
	v_cvt_pk_bf16_f32 v67, v62, v63
	global_store_dwordx4 v[60:61], v[64:67], off sc1
	v_cvt_pk_bf16_f32 v56, v56, v57
	v_cvt_pk_bf16_f32 v57, v58, v59
	v_cvt_pk_bf16_f32 v58, v52, v53
	v_cvt_pk_bf16_f32 v59, v54, v55
	global_store_dwordx4 v[60:61], v[56:59], off offset:256 sc1
.LBB0_316:
	s_and_b64 vcc, exec, s[34:35]
	s_cbranch_vccz .LBB0_318
	v_mul_f32_e32 v36, 0xbfb8aa3b, v36
	v_mul_f32_e32 v41, 0xbfb8aa3b, v41
	v_exp_f32_e32 v36, v36
	v_exp_f32_e32 v41, v41
	v_mul_f32_e32 v37, 0xbfb8aa3b, v37
	v_exp_f32_e32 v37, v37
	v_add_f32_e32 v36, 1.0, v36
	v_add_f32_e32 v41, 1.0, v41
	v_rcp_f32_e32 v36, v36
	v_rcp_f32_e32 v41, v41
	v_add_f32_e32 v37, 1.0, v37
	v_rcp_f32_e32 v37, v37
	v_mul_f32_e32 v44, v44, v36
	v_mul_f32_e32 v36, v49, v41
	v_mul_f32_e32 v41, 0xbfb8aa3b, v42
	v_exp_f32_e32 v41, v41
	v_mul_f32_e32 v40, 0xbfb8aa3b, v40
	v_exp_f32_e32 v40, v40
	v_mul_f32_e32 v38, 0xbfb8aa3b, v38
	v_mul_f32_e32 v42, v45, v37
	v_add_f32_e32 v37, 1.0, v41
	v_mul_f32_e32 v41, 0xbfb8aa3b, v43
	v_exp_f32_e32 v38, v38
	v_exp_f32_e32 v41, v41
	v_mul_f32_e32 v39, 0xbfb8aa3b, v39
	v_exp_f32_e32 v39, v39
	v_add_f32_e32 v40, 1.0, v40
	v_rcp_f32_e32 v40, v40
	v_add_f32_e32 v38, 1.0, v38
	v_add_f32_e32 v41, 1.0, v41
	v_rcp_f32_e32 v38, v38
	v_rcp_f32_e32 v41, v41
	v_add_f32_e32 v39, 1.0, v39
	v_rcp_f32_e32 v37, v37
	v_rcp_f32_e32 v39, v39
	v_mul_f32_e32 v40, v48, v40
	s_lshl_b32 s64, s55, 1
	v_mul_f32_e32 v43, v46, v38
	v_mul_f32_e32 v38, v51, v41
	v_cvt_pk_bf16_f32 v36, v40, v36
	v_lshl_add_u64 v[40:41], v[68:69], 0, s[64:65]
	v_mov_b32_e32 v133, v2
	v_mul_f32_e32 v37, v50, v37
	v_mul_f32_e32 v39, v47, v39
	v_lshl_add_u64 v[40:41], v[40:41], 0, v[132:133]
	v_cvt_pk_bf16_f32 v37, v37, v38
	v_cvt_pk_bf16_f32 v38, v44, v42
	v_cvt_pk_bf16_f32 v39, v43, v39
	global_store_dwordx4 v[40:41], v[36:39], off offset:1536 sc1

.LBB0_327:
	v_cvt_pk_bf16_f32 v48, v48, v49
	v_cvt_pk_bf16_f32 v49, v50, v51
	v_cvt_pk_bf16_f32 v50, v44, v45
	v_lshl_add_u64 v[44:45], v[176:177], 1, v[52:53]
	s_mov_b64 s[34:35], 0
	v_cvt_pk_bf16_f32 v51, v46, v47
	global_store_dwordx4 v[44:45], v[48:51], off sc1
	v_cvt_pk_bf16_f32 v40, v40, v41
	v_cvt_pk_bf16_f32 v41, v42, v43
	v_cvt_pk_bf16_f32 v42, v36, v37
	v_cvt_pk_bf16_f32 v43, v38, v39
	global_store_dwordx4 v[44:45], v[40:43], off offset:256 sc1
.LBB0_328:
	s_and_b64 vcc, exec, s[34:35]
	s_cbranch_vccz .LBB0_330
	v_mul_f32_e32 v20, 0xbfb8aa3b, v20
	v_mul_f32_e32 v25, 0xbfb8aa3b, v25
	v_exp_f32_e32 v20, v20
	v_exp_f32_e32 v25, v25
	v_mul_f32_e32 v21, 0xbfb8aa3b, v21
	v_exp_f32_e32 v21, v21
	v_add_f32_e32 v20, 1.0, v20
	v_add_f32_e32 v25, 1.0, v25
	v_rcp_f32_e32 v20, v20
	v_rcp_f32_e32 v25, v25
	v_add_f32_e32 v21, 1.0, v21
	v_rcp_f32_e32 v21, v21
	v_mul_f32_e32 v28, v28, v20
	v_mul_f32_e32 v20, v33, v25
	v_mul_f32_e32 v25, 0xbfb8aa3b, v26
	v_exp_f32_e32 v25, v25
	v_mul_f32_e32 v24, 0xbfb8aa3b, v24
	v_exp_f32_e32 v24, v24
	v_mul_f32_e32 v22, 0xbfb8aa3b, v22
	v_mul_f32_e32 v26, v29, v21
	v_add_f32_e32 v21, 1.0, v25
	v_mul_f32_e32 v25, 0xbfb8aa3b, v27
	v_exp_f32_e32 v22, v22
	v_exp_f32_e32 v25, v25
	v_mul_f32_e32 v23, 0xbfb8aa3b, v23
	v_exp_f32_e32 v23, v23
	v_add_f32_e32 v24, 1.0, v24
	v_rcp_f32_e32 v24, v24
	v_add_f32_e32 v22, 1.0, v22
	v_add_f32_e32 v25, 1.0, v25
	v_rcp_f32_e32 v22, v22
	v_rcp_f32_e32 v25, v25
	v_add_f32_e32 v23, 1.0, v23
	v_rcp_f32_e32 v21, v21
	v_rcp_f32_e32 v23, v23
	v_mul_f32_e32 v24, v32, v24
	s_lshl_b32 s64, s55, 1
	v_mul_f32_e32 v27, v30, v22
	v_mul_f32_e32 v22, v35, v25
	v_cvt_pk_bf16_f32 v20, v24, v20
	v_lshl_add_u64 v[24:25], v[52:53], 0, s[64:65]
	v_mov_b32_e32 v133, v2
	v_mul_f32_e32 v21, v34, v21
	v_mul_f32_e32 v23, v31, v23
	v_lshl_add_u64 v[24:25], v[24:25], 0, v[132:133]
	v_cvt_pk_bf16_f32 v21, v21, v22
	v_cvt_pk_bf16_f32 v22, v28, v26
	v_cvt_pk_bf16_f32 v23, v27, v23
	global_store_dwordx4 v[24:25], v[20:23], off offset:1536 sc1

.LBB0_339:
	v_cvt_pk_bf16_f32 v32, v32, v33
	v_cvt_pk_bf16_f32 v33, v34, v35
	v_cvt_pk_bf16_f32 v34, v28, v29
	v_lshl_add_u64 v[28:29], v[176:177], 1, v[36:37]
	s_mov_b64 s[34:35], 0
	v_cvt_pk_bf16_f32 v35, v30, v31
	global_store_dwordx4 v[28:29], v[32:35], off sc1
	v_cvt_pk_bf16_f32 v24, v24, v25
	v_cvt_pk_bf16_f32 v25, v26, v27
	v_cvt_pk_bf16_f32 v26, v20, v21
	v_cvt_pk_bf16_f32 v27, v22, v23
	global_store_dwordx4 v[28:29], v[24:27], off offset:256 sc1
.LBB0_340:
	s_and_b64 vcc, exec, s[34:35]
	s_cbranch_vccz .LBB0_342
	v_mul_f32_e32 v4, 0xbfb8aa3b, v4
	v_mul_f32_e32 v9, 0xbfb8aa3b, v9
	v_exp_f32_e32 v4, v4
	v_exp_f32_e32 v9, v9
	v_mul_f32_e32 v5, 0xbfb8aa3b, v5
	v_exp_f32_e32 v5, v5
	v_add_f32_e32 v4, 1.0, v4
	v_add_f32_e32 v9, 1.0, v9
	v_rcp_f32_e32 v4, v4
	v_rcp_f32_e32 v9, v9
	v_add_f32_e32 v5, 1.0, v5
	v_rcp_f32_e32 v5, v5
	v_mul_f32_e32 v12, v12, v4
	v_mul_f32_e32 v4, v17, v9
	v_mul_f32_e32 v9, 0xbfb8aa3b, v10
	v_exp_f32_e32 v9, v9
	v_mul_f32_e32 v8, 0xbfb8aa3b, v8
	v_exp_f32_e32 v8, v8
	v_mul_f32_e32 v6, 0xbfb8aa3b, v6
	v_mul_f32_e32 v10, v13, v5
	v_add_f32_e32 v5, 1.0, v9
	v_mul_f32_e32 v9, 0xbfb8aa3b, v11
	v_exp_f32_e32 v6, v6
	v_exp_f32_e32 v9, v9
	v_mul_f32_e32 v7, 0xbfb8aa3b, v7
	v_exp_f32_e32 v7, v7
	v_add_f32_e32 v8, 1.0, v8
	v_rcp_f32_e32 v8, v8
	v_add_f32_e32 v6, 1.0, v6
	v_add_f32_e32 v9, 1.0, v9
	v_rcp_f32_e32 v6, v6
	v_rcp_f32_e32 v9, v9
	v_add_f32_e32 v7, 1.0, v7
	v_rcp_f32_e32 v5, v5
	v_rcp_f32_e32 v7, v7
	v_mul_f32_e32 v8, v16, v8
	s_lshl_b32 s64, s55, 1
	v_mul_f32_e32 v11, v14, v6
	v_mul_f32_e32 v6, v19, v9
	v_cvt_pk_bf16_f32 v4, v8, v4
	v_lshl_add_u64 v[8:9], v[36:37], 0, s[64:65]
	v_mov_b32_e32 v133, v2
	v_mul_f32_e32 v5, v18, v5
	v_mul_f32_e32 v7, v15, v7
	v_lshl_add_u64 v[8:9], v[8:9], 0, v[132:133]
	v_cvt_pk_bf16_f32 v5, v5, v6
	v_cvt_pk_bf16_f32 v6, v12, v10
	v_cvt_pk_bf16_f32 v7, v11, v7
	global_store_dwordx4 v[8:9], v[4:7], off offset:1536 sc1

.LBB0_416:
	s_or_b64 exec, exec, s[34:35]
	s_waitcnt vmcnt(4)
	v_add_f32_e32 v16, v98, v16
	s_waitcnt vmcnt(3)
	v_lshlrev_b32_e32 v20, 16, v58
	v_mul_f32_e32 v16, v16, v20
	v_add_f32_e32 v17, v98, v17
	v_and_b32_e32 v20, 0xffff0000, v58
	v_mul_f32_e32 v17, v17, v20
	v_cvt_pk_bf16_f32 v16, v16, v17
	v_add_f32_e32 v17, v98, v18
	v_lshlrev_b32_e32 v18, 16, v59
	v_mul_f32_e32 v17, v17, v18
	v_add_f32_e32 v18, v98, v19
	v_and_b32_e32 v19, 0xffff0000, v59
	v_mul_f32_e32 v18, v18, v19
	v_cvt_pk_bf16_f32 v17, v17, v18
	v_lshlrev_b32_e32 v18, 12, v99
	v_mov_b32_e32 v19, v2
	v_lshl_add_u64 v[18:19], v[48:49], 0, v[18:19]
	global_store_dwordx2 v[18:19], v[16:17], off offset:3072 sc1
	v_add_f32_e32 v12, v98, v12
	s_waitcnt vmcnt(3)
	v_lshlrev_b32_e32 v16, 16, v56
	v_mul_f32_e32 v12, v12, v16
	v_add_f32_e32 v13, v98, v13
	v_and_b32_e32 v16, 0xffff0000, v56
	v_mul_f32_e32 v13, v13, v16
	v_cvt_pk_bf16_f32 v12, v12, v13
	v_add_f32_e32 v13, v98, v14
	v_lshlrev_b32_e32 v14, 16, v57
	v_mul_f32_e32 v13, v13, v14
	v_add_f32_e32 v14, v98, v15
	v_and_b32_e32 v15, 0xffff0000, v57
	v_mul_f32_e32 v14, v14, v15
	v_cvt_pk_bf16_f32 v13, v13, v14
	global_store_dwordx2 v[18:19], v[12:13], off offset:3104 sc1
	v_add_f32_e32 v8, v98, v8
	s_waitcnt vmcnt(3)
	v_lshlrev_b32_e32 v12, 16, v54
	v_mul_f32_e32 v8, v8, v12
	v_add_f32_e32 v9, v98, v9
	v_and_b32_e32 v12, 0xffff0000, v54
	v_mul_f32_e32 v9, v9, v12
	v_cvt_pk_bf16_f32 v8, v8, v9
	v_add_f32_e32 v9, v98, v10
	v_lshlrev_b32_e32 v10, 16, v55
	v_mul_f32_e32 v9, v9, v10
	v_add_f32_e32 v10, v98, v11
	v_and_b32_e32 v11, 0xffff0000, v55
	v_mul_f32_e32 v10, v10, v11
	v_cvt_pk_bf16_f32 v9, v9, v10
	global_store_dwordx2 v[18:19], v[8:9], off offset:3136 sc1
	v_add_f32_e32 v4, v98, v4
	s_waitcnt vmcnt(3)
	v_lshlrev_b32_e32 v8, 16, v52
	v_mul_f32_e32 v4, v4, v8
	v_add_f32_e32 v5, v98, v5
	v_and_b32_e32 v8, 0xffff0000, v52
	v_mul_f32_e32 v5, v5, v8
	v_cvt_pk_bf16_f32 v4, v4, v5
	v_add_f32_e32 v5, v98, v6
	v_lshlrev_b32_e32 v6, 16, v53
	s_add_i32 s36, s36, 1
	v_mul_f32_e32 v5, v5, v6
	v_add_f32_e32 v6, v98, v7
	v_and_b32_e32 v7, 0xffff0000, v53
	s_cmp_lg_u32 s36, 4
	v_mul_f32_e32 v6, v6, v7
	v_cvt_pk_bf16_f32 v5, v5, v6
	global_store_dwordx2 v[18:19], v[4:5], off offset:3168 sc1
	s_cbranch_scc0 .LBB0_423

.LBB0_467:
	v_add_u32_e32 v6, -16, v5
	v_add_u32_e32 v20, s34, v4
	ds_read_b128 v[6:9], v6
	ds_read_b128 v[10:13], v5
	ds_read_b128 v[14:17], v20
	s_addk_i32 s34, 0x410
	v_add_u32_e32 v5, 0x800, v5
	s_cmpk_lg_i32 s34, 0x7df0
	s_waitcnt lgkmcnt(0)
	v_lshlrev_b32_e32 v18, 16, v14
	v_and_b32_e32 v19, 0xffff0000, v14
	v_lshlrev_b32_e32 v14, 16, v15
	v_and_b32_e32 v15, 0xffff0000, v15
	v_pk_fma_f32 v[58:59], v[8:9], v[14:15], v[58:59]
	v_lshlrev_b32_e32 v14, 16, v16
	v_and_b32_e32 v15, 0xffff0000, v16
	v_pk_fma_f32 v[30:31], v[10:11], v[14:15], v[30:31]
	v_lshlrev_b32_e32 v14, 16, v17
	v_and_b32_e32 v15, 0xffff0000, v17
	v_pk_fma_f32 v[28:29], v[12:13], v[14:15], v[28:29]
	ds_read_b128 v[14:17], v20 offset:1040
	v_pk_fma_f32 v[60:61], v[6:7], v[18:19], v[60:61]
	s_waitcnt lgkmcnt(0)
	v_lshlrev_b32_e32 v18, 16, v14
	v_and_b32_e32 v19, 0xffff0000, v14
	v_lshlrev_b32_e32 v14, 16, v15
	v_and_b32_e32 v15, 0xffff0000, v15
	v_pk_fma_f32 v[56:57], v[8:9], v[14:15], v[56:57]
	v_lshlrev_b32_e32 v14, 16, v16
	v_and_b32_e32 v15, 0xffff0000, v16
	v_pk_fma_f32 v[52:53], v[10:11], v[14:15], v[52:53]
	v_lshlrev_b32_e32 v14, 16, v17
	v_and_b32_e32 v15, 0xffff0000, v17
	v_pk_fma_f32 v[50:51], v[12:13], v[14:15], v[50:51]
	ds_read_b128 v[14:17], v20 offset:2080
	v_pk_fma_f32 v[54:55], v[6:7], v[18:19], v[54:55]
	s_waitcnt lgkmcnt(0)
	v_lshlrev_b32_e32 v18, 16, v14
	v_and_b32_e32 v19, 0xffff0000, v14
	v_lshlrev_b32_e32 v14, 16, v15
	v_and_b32_e32 v15, 0xffff0000, v15
	v_pk_fma_f32 v[44:45], v[8:9], v[14:15], v[44:45]
	v_lshlrev_b32_e32 v14, 16, v16
	v_and_b32_e32 v15, 0xffff0000, v16
	v_pk_fma_f32 v[42:43], v[10:11], v[14:15], v[42:43]
	v_lshlrev_b32_e32 v14, 16, v17
	v_and_b32_e32 v15, 0xffff0000, v17
	v_pk_fma_f32 v[40:41], v[12:13], v[14:15], v[40:41]
	ds_read_b128 v[14:17], v20 offset:3120
	v_pk_fma_f32 v[46:47], v[6:7], v[18:19], v[46:47]
	s_waitcnt lgkmcnt(0)
	v_lshlrev_b32_e32 v18, 16, v14
	v_and_b32_e32 v19, 0xffff0000, v14
	v_pk_fma_f32 v[38:39], v[6:7], v[18:19], v[38:39]
	v_lshlrev_b32_e32 v6, 16, v15
	v_and_b32_e32 v7, 0xffff0000, v15
	v_pk_fma_f32 v[36:37], v[8:9], v[6:7], v[36:37]
	v_lshlrev_b32_e32 v6, 16, v16
	v_and_b32_e32 v7, 0xffff0000, v16
	v_pk_fma_f32 v[34:35], v[10:11], v[6:7], v[34:35]
	v_lshlrev_b32_e32 v6, 16, v17
	v_and_b32_e32 v7, 0xffff0000, v17
	v_pk_fma_f32 v[32:33], v[12:13], v[6:7], v[32:33]
	s_cbranch_scc1 .LBB0_467
	s_lshl_b32 s38, s96, 2
	s_add_u32 s34, s58, s38
	s_addc_u32 s35, s59, 0
	s_add_u32 s36, s60, s38
	s_addc_u32 s37, s61, 0
	s_add_u32 s38, s62, s38
	s_addc_u32 s39, s63, 0
	global_load_dwordx4 v[20:23], v68, s[34:35] offset:16
	global_load_dwordx4 v[24:27], v68, s[34:35]
	global_load_dwordx4 v[4:7], v68, s[36:37] offset:16
	global_load_dwordx4 v[12:15], v68, s[36:37]
	global_load_dwordx4 v[8:11], v68, s[38:39] offset:16
	global_load_dwordx4 v[16:19], v68, s[38:39]
	s_addk_i32 s64, 0xc000
	v_add_u32_e32 v48, s64, v1
	v_mov_b32_e32 v49, v2
	s_waitcnt vmcnt(5)
	v_pk_add_f32 v[28:29], v[28:29], v[22:23]
	s_waitcnt vmcnt(4)
	v_pk_add_f32 v[58:59], v[58:59], v[26:27]
	v_pk_add_f32 v[60:61], v[60:61], v[24:25]
	v_pk_add_f32 v[30:31], v[30:31], v[20:21]
	v_pk_mov_b32 v[62:63], v[60:61], v[58:59] op_sel:[1,0]
	v_mov_b32_e32 v64, v60
	v_mov_b32_e32 v65, v59
	v_pk_add_f32 v[62:63], v[62:63], v[64:65]
	v_mov_b32_e32 v64, v28
	v_mov_b32_e32 v65, v30
	v_mov_b32_e32 v66, v29
	v_mov_b32_e32 v67, v31
	v_pk_add_f32 v[64:65], v[64:65], v[66:67]
	v_add_f32_e32 v1, v62, v63
	v_add_f32_e32 v1, v1, v65
	v_add_f32_e32 v1, v64, v1
	v_pk_add_f32 v[50:51], v[50:51], v[22:23]
	v_pk_add_f32 v[52:53], v[52:53], v[20:21]
	v_add_f32_dpp v1, v1, v1 row_shr:1 row_mask:0xf bank_mask:0xf bound_ctrl:1
	v_pk_add_f32 v[40:41], v[40:41], v[22:23]
	v_pk_add_f32 v[42:43], v[42:43], v[20:21]
	v_add_f32_dpp v1, v1, v1 row_shr:2 row_mask:0xf bank_mask:0xf bound_ctrl:1
	v_pk_add_f32 v[22:23], v[32:33], v[22:23]
	v_pk_add_f32 v[20:21], v[34:35], v[20:21]
	v_add_f32_dpp v1, v1, v1 row_shr:4 row_mask:0xf bank_mask:0xf bound_ctrl:1
	v_mov_b32_e32 v32, v23
	v_mov_b32_e32 v33, v21
	v_add_f32_dpp v1, v1, v1 row_shr:8 row_mask:0xf bank_mask:0xf bound_ctrl:1
	s_nop 1
	v_mov_b32_dpp v49, v1 row_bcast:15 row_mask:0xa bank_mask:0xf
	v_add_f32_e32 v1, v1, v49
	v_mov_b32_e32 v49, v2
	s_nop 1
	v_mov_b32_dpp v49, v1 row_bcast:31 row_mask:0xc bank_mask:0xf
	v_add_f32_e32 v1, v1, v49
	s_nop 0
	v_readlane_b32 s34, v1, 63
	s_nop 1
	v_fmac_f32_e32 v59, s34, v222
	v_fmac_f32_e32 v61, s34, v222
	v_fma_f32 v31, s34, v222, v31
	v_fmac_f32_e32 v30, s34, v222
	v_fma_f32 v29, s34, v222, v29
	v_fmac_f32_e32 v28, s34, v222
	v_fma_f32 v58, s34, v222, v58
	v_fma_f32 v60, s34, v222, v60
	v_mul_f32_e32 v1, v61, v61
	v_mul_f32_e32 v49, v59, v59
	v_pk_mul_f32 v[62:63], v[28:29], v[28:29]
	v_pk_mul_f32 v[64:65], v[30:31], v[30:31]
	v_fmac_f32_e32 v1, v60, v60
	v_fmac_f32_e32 v49, v58, v58
	v_mov_b32_e32 v66, v62
	v_mov_b32_e32 v67, v64
	v_mov_b32_e32 v64, v63
	v_add_f32_e32 v1, v1, v49
	v_pk_add_f32 v[62:63], v[66:67], v[64:65]
	v_mov_b32_e32 v49, v2
	v_add_f32_e32 v1, v63, v1
	v_add_f32_e32 v1, v62, v1
	s_nop 1
	v_add_f32_dpp v1, v1, v1 row_shr:1 row_mask:0xf bank_mask:0xf bound_ctrl:1
	s_nop 1
	v_add_f32_dpp v1, v1, v1 row_shr:2 row_mask:0xf bank_mask:0xf bound_ctrl:1
	s_nop 1
	v_add_f32_dpp v1, v1, v1 row_shr:4 row_mask:0xf bank_mask:0xf bound_ctrl:1
	s_nop 1
	v_add_f32_dpp v1, v1, v1 row_shr:8 row_mask:0xf bank_mask:0xf bound_ctrl:1
	s_nop 1
	v_mov_b32_dpp v49, v1 row_bcast:15 row_mask:0xa bank_mask:0xf
	v_add_f32_e32 v1, v1, v49
	v_mov_b32_e32 v49, v2
	s_nop 1
	v_mov_b32_dpp v49, v1 row_bcast:31 row_mask:0xc bank_mask:0xf
	v_add_f32_e32 v1, v1, v49
	s_nop 0
	v_readlane_b32 s34, v1, 63
	s_nop 1
	v_fma_f32 v1, s34, v223, v159
	v_rsq_f32_e32 v62, v1
	s_nop 0
	v_pk_mul_f32 v[60:61], v[60:61], v[62:63] op_sel_hi:[1,0]
	s_waitcnt vmcnt(0)
	v_pk_fma_f32 v[60:61], v[12:13], v[60:61], v[16:17]
	v_pk_mul_f32 v[30:31], v[30:31], v[62:63] op_sel_hi:[1,0]
	v_mul_f32_e32 v1, 0xbfb8aa3b, v60
	v_exp_f32_e32 v1, v1
	v_pk_fma_f32 v[30:31], v[4:5], v[30:31], v[8:9]
	v_pk_mul_f32 v[58:59], v[58:59], v[62:63] op_sel_hi:[1,0]
	v_pk_mul_f32 v[28:29], v[28:29], v[62:63] op_sel_hi:[1,0]
	v_add_f32_e32 v1, 1.0, v1
	v_rcp_f32_e32 v1, v1
	v_pk_fma_f32 v[58:59], v[14:15], v[58:59], v[18:19]
	v_pk_fma_f32 v[28:29], v[6:7], v[28:29], v[10:11]
	v_mul_f32_e32 v49, 0xbfb8aa3b, v30
	v_mul_f32_e32 v1, v60, v1
	v_mul_f32_e32 v60, 0xbfb8aa3b, v31
	v_exp_f32_e32 v60, v60
	v_exp_f32_e32 v49, v49
	v_add_f32_e32 v60, 1.0, v60
	v_rcp_f32_e32 v60, v60
	v_add_f32_e32 v49, 1.0, v49
	v_rcp_f32_e32 v49, v49
	v_mul_f32_e32 v31, v31, v60
	v_mul_f32_e32 v60, 0xbfb8aa3b, v58
	v_exp_f32_e32 v60, v60
	v_mul_f32_e32 v30, v30, v49
	v_mul_f32_e32 v49, 0xbfb8aa3b, v61
	v_exp_f32_e32 v49, v49
	v_add_f32_e32 v60, 1.0, v60
	v_rcp_f32_e32 v60, v60
	v_add_f32_e32 v49, 1.0, v49
	v_rcp_f32_e32 v49, v49
	v_mul_f32_e32 v58, v58, v60
	v_mul_f32_e32 v60, 0xbfb8aa3b, v28
	v_exp_f32_e32 v60, v60
	v_mul_f32_e32 v49, v61, v49
	v_add_f32_e32 v60, 1.0, v60
	v_rcp_f32_e32 v60, v60
	s_nop 0
	v_mul_f32_e32 v60, v28, v60
	v_mul_f32_e32 v28, 0xbfb8aa3b, v59
	v_exp_f32_e32 v28, v28
	s_nop 0
	v_add_f32_e32 v28, 1.0, v28
	v_rcp_f32_e32 v28, v28
	s_nop 0
	v_mul_f32_e32 v59, v59, v28
	v_mul_f32_e32 v28, 0xbfb8aa3b, v29
	v_exp_f32_e32 v28, v28
	s_nop 0
	v_add_f32_e32 v28, 1.0, v28
	v_rcp_f32_e32 v28, v28
	s_nop 0
	v_mul_f32_e32 v61, v29, v28
	v_cvt_pk_bf16_f32 v28, v1, v49
	v_ashrrev_i32_e32 v49, 31, v48
	v_cvt_pk_bf16_f32 v29, v58, v59
	v_lshlrev_b64 v[58:59], 12, v[48:49]
	v_lshl_add_u64 v[58:59], s[26:27], 0, v[58:59]
	v_mov_b32_e32 v1, v2
	v_cvt_pk_bf16_f32 v30, v30, v31
	v_cvt_pk_bf16_f32 v31, v60, v61
	v_lshl_add_u64 v[58:59], v[58:59], 0, v[0:1]
	global_store_dwordx4 v[58:59], v[28:31], off offset:2048 sc1
	v_mov_b32_e32 v58, v51
	v_mov_b32_e32 v59, v53
	v_pk_add_f32 v[28:29], v[56:57], v[26:27]
	v_pk_add_f32 v[30:31], v[54:55], v[24:25]
	v_mov_b32_e32 v57, v29
	v_pk_mov_b32 v[54:55], v[30:31], v[28:29] op_sel:[1,0]
	v_mov_b32_e32 v56, v30
	v_pk_add_f32 v[54:55], v[54:55], v[56:57]
	v_mov_b32_e32 v56, v50
	v_mov_b32_e32 v57, v52
	v_pk_add_f32 v[56:57], v[56:57], v[58:59]
	v_add_f32_e32 v49, v54, v55
	v_add_f32_e32 v49, v49, v57
	v_add_f32_e32 v49, v56, v49
	v_mov_b32_e32 v54, v2
	s_nop 0
	v_add_f32_dpp v49, v49, v49 row_shr:1 row_mask:0xf bank_mask:0xf bound_ctrl:1
	s_nop 1
	v_add_f32_dpp v49, v49, v49 row_shr:2 row_mask:0xf bank_mask:0xf bound_ctrl:1
	s_nop 1
	v_add_f32_dpp v49, v49, v49 row_shr:4 row_mask:0xf bank_mask:0xf bound_ctrl:1
	s_nop 1
	v_add_f32_dpp v49, v49, v49 row_shr:8 row_mask:0xf bank_mask:0xf bound_ctrl:1
	s_nop 1
	v_mov_b32_dpp v54, v49 row_bcast:15 row_mask:0xa bank_mask:0xf
	v_add_f32_e32 v49, v49, v54
	v_mov_b32_e32 v54, v2
	s_nop 1
	v_mov_b32_dpp v54, v49 row_bcast:31 row_mask:0xc bank_mask:0xf
	v_add_f32_e32 v49, v49, v54
	s_nop 0
	v_readlane_b32 s34, v49, 63
	s_nop 1
	v_fmac_f32_e32 v29, s34, v222
	v_fmac_f32_e32 v31, s34, v222
	v_fma_f32 v28, s34, v222, v28
	v_fma_f32 v30, s34, v222, v30
	v_mul_f32_e32 v49, v31, v31
	v_mul_f32_e32 v54, v29, v29
	v_fma_f32 v53, s34, v222, v53
	v_fmac_f32_e32 v52, s34, v222
	v_fma_f32 v51, s34, v222, v51
	v_fmac_f32_e32 v50, s34, v222
	v_fmac_f32_e32 v49, v30, v30
	v_fmac_f32_e32 v54, v28, v28
	v_add_f32_e32 v49, v49, v54
	v_pk_mul_f32 v[54:55], v[50:51], v[50:51]
	v_pk_mul_f32 v[56:57], v[52:53], v[52:53]
	v_mov_b32_e32 v58, v54
	v_mov_b32_e32 v59, v56
	v_mov_b32_e32 v56, v55
	v_pk_add_f32 v[54:55], v[58:59], v[56:57]
	s_nop 0
	v_add_f32_e32 v49, v55, v49
	v_add_f32_e32 v49, v54, v49
	v_mov_b32_e32 v54, v2
	s_nop 0
	v_add_f32_dpp v49, v49, v49 row_shr:1 row_mask:0xf bank_mask:0xf bound_ctrl:1
	s_nop 1
	v_add_f32_dpp v49, v49, v49 row_shr:2 row_mask:0xf bank_mask:0xf bound_ctrl:1
	s_nop 1
	v_add_f32_dpp v49, v49, v49 row_shr:4 row_mask:0xf bank_mask:0xf bound_ctrl:1
	s_nop 1
	v_add_f32_dpp v49, v49, v49 row_shr:8 row_mask:0xf bank_mask:0xf bound_ctrl:1
	s_nop 1
	v_mov_b32_dpp v54, v49 row_bcast:15 row_mask:0xa bank_mask:0xf
	v_add_f32_e32 v49, v49, v54
	v_mov_b32_e32 v54, v2
	s_nop 1
	v_mov_b32_dpp v54, v49 row_bcast:31 row_mask:0xc bank_mask:0xf
	v_add_f32_e32 v49, v49, v54
	s_nop 0
	v_readlane_b32 s34, v49, 63
	s_nop 1
	v_fma_f32 v49, s34, v223, v159
	v_rsq_f32_e32 v54, v49
	s_nop 0
	v_pk_mul_f32 v[30:31], v[30:31], v[54:55] op_sel_hi:[1,0]
	s_nop 0
	v_pk_fma_f32 v[30:31], v[12:13], v[30:31], v[16:17]
	v_pk_mul_f32 v[52:53], v[52:53], v[54:55] op_sel_hi:[1,0]
	v_mul_f32_e32 v49, 0xbfb8aa3b, v30
	v_exp_f32_e32 v49, v49
	v_pk_fma_f32 v[52:53], v[4:5], v[52:53], v[8:9]
	v_pk_mul_f32 v[28:29], v[28:29], v[54:55] op_sel_hi:[1,0]
	v_pk_mul_f32 v[50:51], v[50:51], v[54:55] op_sel_hi:[1,0]
	v_add_f32_e32 v49, 1.0, v49
	v_rcp_f32_e32 v49, v49
	v_pk_fma_f32 v[28:29], v[14:15], v[28:29], v[18:19]
	v_pk_fma_f32 v[50:51], v[6:7], v[50:51], v[10:11]
	v_mul_f32_e32 v30, v30, v49
	v_mul_f32_e32 v49, 0xbfb8aa3b, v52
	v_exp_f32_e32 v49, v49
	s_nop 0
	v_add_f32_e32 v49, 1.0, v49
	v_rcp_f32_e32 v49, v49
	s_nop 0
	v_mul_f32_e32 v49, v52, v49
	v_mul_f32_e32 v52, 0xbfb8aa3b, v31
	v_exp_f32_e32 v52, v52
	s_nop 0
	v_add_f32_e32 v52, 1.0, v52
	v_rcp_f32_e32 v52, v52
	s_nop 0
	v_mul_f32_e32 v31, v31, v52
	v_mul_f32_e32 v52, 0xbfb8aa3b, v53
	v_exp_f32_e32 v52, v52
	s_nop 0
	v_add_f32_e32 v52, 1.0, v52
	v_rcp_f32_e32 v52, v52
	s_nop 0
	v_mul_f32_e32 v52, v53, v52
	v_mul_f32_e32 v53, 0xbfb8aa3b, v28
	v_exp_f32_e32 v53, v53
	s_nop 0
	v_add_f32_e32 v53, 1.0, v53
	v_rcp_f32_e32 v53, v53
	s_nop 0
	v_mul_f32_e32 v53, v28, v53
	v_mul_f32_e32 v28, 0xbfb8aa3b, v50
	v_exp_f32_e32 v28, v28
	s_nop 0
	v_add_f32_e32 v28, 1.0, v28
	v_rcp_f32_e32 v28, v28
	s_nop 0
	v_mul_f32_e32 v50, v50, v28
	v_mul_f32_e32 v28, 0xbfb8aa3b, v29
	v_exp_f32_e32 v28, v28
	s_nop 0
	v_add_f32_e32 v28, 1.0, v28
	v_rcp_f32_e32 v28, v28
	s_nop 0
	v_mul_f32_e32 v29, v29, v28
	v_mul_f32_e32 v28, 0xbfb8aa3b, v51
	v_exp_f32_e32 v28, v28
	s_nop 0
	v_add_f32_e32 v28, 1.0, v28
	v_rcp_f32_e32 v28, v28
	s_nop 0
	v_mul_f32_e32 v51, v51, v28
	v_cvt_pk_bf16_f32 v28, v30, v31
	v_cvt_pk_bf16_f32 v29, v53, v29
	v_cvt_pk_bf16_f32 v30, v49, v52
	v_cvt_pk_bf16_f32 v31, v50, v51
	v_or_b32_e32 v50, 1, v48
	v_ashrrev_i32_e32 v51, 31, v50
	v_lshlrev_b64 v[50:51], 12, v[50:51]
	v_lshl_add_u64 v[50:51], s[26:27], 0, v[50:51]
	v_lshl_add_u64 v[50:51], v[50:51], 0, v[0:1]
	global_store_dwordx4 v[50:51], v[28:31], off offset:2048 sc1
	v_mov_b32_e32 v50, v41
	v_mov_b32_e32 v51, v43
	v_pk_add_f32 v[28:29], v[44:45], v[26:27]
	v_pk_add_f32 v[30:31], v[46:47], v[24:25]
	v_mov_b32_e32 v47, v29
	v_pk_mov_b32 v[44:45], v[30:31], v[28:29] op_sel:[1,0]
	v_mov_b32_e32 v46, v30
	v_pk_add_f32 v[44:45], v[44:45], v[46:47]
	v_mov_b32_e32 v46, v40
	v_mov_b32_e32 v47, v42
	v_pk_add_f32 v[46:47], v[46:47], v[50:51]
	v_add_f32_e32 v44, v44, v45
	v_add_f32_e32 v44, v44, v47
	v_add_f32_e32 v44, v46, v44
	v_mov_b32_e32 v45, v2
	v_pk_add_f32 v[26:27], v[36:37], v[26:27]
	v_add_f32_dpp v44, v44, v44 row_shr:1 row_mask:0xf bank_mask:0xf bound_ctrl:1
	v_pk_add_f32 v[24:25], v[38:39], v[24:25]
	s_nop 0
	v_add_f32_dpp v44, v44, v44 row_shr:2 row_mask:0xf bank_mask:0xf bound_ctrl:1
	s_nop 1
	v_add_f32_dpp v44, v44, v44 row_shr:4 row_mask:0xf bank_mask:0xf bound_ctrl:1
	s_nop 1
	v_add_f32_dpp v44, v44, v44 row_shr:8 row_mask:0xf bank_mask:0xf bound_ctrl:1
	s_nop 1
	v_mov_b32_dpp v45, v44 row_bcast:15 row_mask:0xa bank_mask:0xf
	v_add_f32_e32 v44, v44, v45
	v_mov_b32_e32 v45, v2
	s_nop 1
	v_mov_b32_dpp v45, v44 row_bcast:31 row_mask:0xc bank_mask:0xf
	v_add_f32_e32 v44, v44, v45
	s_nop 0
	v_readlane_b32 s34, v44, 63
	s_nop 1
	v_fmac_f32_e32 v29, s34, v222
	v_fmac_f32_e32 v31, s34, v222
	v_fma_f32 v28, s34, v222, v28
	v_fma_f32 v30, s34, v222, v30
	v_mul_f32_e32 v44, v31, v31
	v_mul_f32_e32 v45, v29, v29
	v_fma_f32 v43, s34, v222, v43
	v_fmac_f32_e32 v42, s34, v222
	v_fma_f32 v41, s34, v222, v41
	v_fmac_f32_e32 v40, s34, v222
	v_fmac_f32_e32 v44, v30, v30
	v_fmac_f32_e32 v45, v28, v28
	v_add_f32_e32 v49, v44, v45
	v_pk_mul_f32 v[44:45], v[40:41], v[40:41]
	v_pk_mul_f32 v[46:47], v[42:43], v[42:43]
	v_mov_b32_e32 v50, v44
	v_mov_b32_e32 v51, v46
	v_mov_b32_e32 v46, v45
	v_pk_add_f32 v[44:45], v[50:51], v[46:47]
	s_nop 0
	v_add_f32_e32 v45, v45, v49
	v_add_f32_e32 v44, v44, v45
	v_mov_b32_e32 v45, v2
	s_nop 0
	v_add_f32_dpp v44, v44, v44 row_shr:1 row_mask:0xf bank_mask:0xf bound_ctrl:1
	s_nop 1
	v_add_f32_dpp v44, v44, v44 row_shr:2 row_mask:0xf bank_mask:0xf bound_ctrl:1
	s_nop 1
	v_add_f32_dpp v44, v44, v44 row_shr:4 row_mask:0xf bank_mask:0xf bound_ctrl:1
	s_nop 1
	v_add_f32_dpp v44, v44, v44 row_shr:8 row_mask:0xf bank_mask:0xf bound_ctrl:1
	s_nop 1
	v_mov_b32_dpp v45, v44 row_bcast:15 row_mask:0xa bank_mask:0xf
	v_add_f32_e32 v44, v44, v45
	v_mov_b32_e32 v45, v2
	s_nop 1
	v_mov_b32_dpp v45, v44 row_bcast:31 row_mask:0xc bank_mask:0xf
	v_add_f32_e32 v44, v44, v45
	s_nop 0
	v_readlane_b32 s34, v44, 63
	s_nop 1
	v_fma_f32 v44, s34, v223, v159
	v_rsq_f32_e32 v44, v44
	s_nop 0
	v_pk_mul_f32 v[30:31], v[30:31], v[44:45] op_sel_hi:[1,0]
	s_nop 0
	v_pk_fma_f32 v[30:31], v[12:13], v[30:31], v[16:17]
	v_pk_mul_f32 v[28:29], v[28:29], v[44:45] op_sel_hi:[1,0]
	v_pk_mul_f32 v[42:43], v[42:43], v[44:45] op_sel_hi:[1,0]
	v_pk_mul_f32 v[40:41], v[40:41], v[44:45] op_sel_hi:[1,0]
	v_mul_f32_e32 v44, 0xbfb8aa3b, v30
	v_exp_f32_e32 v44, v44
	v_pk_fma_f32 v[42:43], v[4:5], v[42:43], v[8:9]
	v_pk_fma_f32 v[28:29], v[14:15], v[28:29], v[18:19]
	v_pk_fma_f32 v[40:41], v[6:7], v[40:41], v[10:11]
	v_add_f32_e32 v44, 1.0, v44
	v_rcp_f32_e32 v44, v44
	s_nop 0
	v_mul_f32_e32 v30, v30, v44
	v_mul_f32_e32 v44, 0xbfb8aa3b, v42
	v_exp_f32_e32 v44, v44
	s_nop 0
	v_add_f32_e32 v44, 1.0, v44
	v_rcp_f32_e32 v44, v44
	s_nop 0
	v_mul_f32_e32 v42, v42, v44
	v_mul_f32_e32 v44, 0xbfb8aa3b, v31
	v_exp_f32_e32 v44, v44
	s_nop 0
	v_add_f32_e32 v44, 1.0, v44
	v_rcp_f32_e32 v44, v44
	s_nop 0
	v_mul_f32_e32 v31, v31, v44
	v_mul_f32_e32 v44, 0xbfb8aa3b, v43
	v_exp_f32_e32 v44, v44
	s_nop 0
	v_add_f32_e32 v44, 1.0, v44
	v_rcp_f32_e32 v44, v44
	s_nop 0
	v_mul_f32_e32 v43, v43, v44
	v_mul_f32_e32 v44, 0xbfb8aa3b, v28
	v_exp_f32_e32 v44, v44
	s_nop 0
	v_add_f32_e32 v44, 1.0, v44
	v_rcp_f32_e32 v44, v44
	s_nop 0
	v_mul_f32_e32 v44, v28, v44
	v_mul_f32_e32 v28, 0xbfb8aa3b, v40
	v_exp_f32_e32 v28, v28
	s_nop 0
	v_add_f32_e32 v28, 1.0, v28
	v_rcp_f32_e32 v28, v28
	s_nop 0
	v_mul_f32_e32 v40, v40, v28
	v_mul_f32_e32 v28, 0xbfb8aa3b, v29
	v_exp_f32_e32 v28, v28
	s_nop 0
	v_add_f32_e32 v28, 1.0, v28
	v_rcp_f32_e32 v28, v28
	s_nop 0
	v_mul_f32_e32 v29, v29, v28
	v_mul_f32_e32 v28, 0xbfb8aa3b, v41
	v_exp_f32_e32 v28, v28
	s_nop 0
	v_add_f32_e32 v28, 1.0, v28
	v_rcp_f32_e32 v28, v28
	s_nop 0
	v_mul_f32_e32 v41, v41, v28
	v_cvt_pk_bf16_f32 v28, v30, v31
	v_cvt_pk_bf16_f32 v29, v44, v29
	v_cvt_pk_bf16_f32 v30, v42, v43
	v_cvt_pk_bf16_f32 v31, v40, v41
	v_or_b32_e32 v40, 2, v48
	v_ashrrev_i32_e32 v41, 31, v40
	v_lshlrev_b64 v[40:41], 12, v[40:41]
	v_lshl_add_u64 v[40:41], s[26:27], 0, v[40:41]
	v_lshl_add_u64 v[40:41], v[40:41], 0, v[0:1]
	global_store_dwordx4 v[40:41], v[28:31], off offset:2048 sc1
	s_nop 1
	v_pk_mov_b32 v[28:29], v[24:25], v[26:27] op_sel:[1,0]
	v_mov_b32_e32 v30, v24
	v_mov_b32_e32 v31, v27
	v_pk_add_f32 v[28:29], v[28:29], v[30:31]
	v_mov_b32_e32 v30, v22
	v_mov_b32_e32 v31, v20
	v_pk_add_f32 v[30:31], v[30:31], v[32:33]
	v_add_f32_e32 v28, v28, v29
	v_add_f32_e32 v28, v28, v31
	v_add_f32_e32 v28, v30, v28
	v_mov_b32_e32 v29, v2
	s_nop 0
	v_add_f32_dpp v28, v28, v28 row_shr:1 row_mask:0xf bank_mask:0xf bound_ctrl:1
	s_nop 1
	v_add_f32_dpp v28, v28, v28 row_shr:2 row_mask:0xf bank_mask:0xf bound_ctrl:1
	s_nop 1
	v_add_f32_dpp v28, v28, v28 row_shr:4 row_mask:0xf bank_mask:0xf bound_ctrl:1
	s_nop 1
	v_add_f32_dpp v28, v28, v28 row_shr:8 row_mask:0xf bank_mask:0xf bound_ctrl:1
	s_nop 1
	v_mov_b32_dpp v29, v28 row_bcast:15 row_mask:0xa bank_mask:0xf
	v_add_f32_e32 v28, v28, v29
	v_mov_b32_e32 v29, v2
	s_nop 1
	v_mov_b32_dpp v29, v28 row_bcast:31 row_mask:0xc bank_mask:0xf
	v_add_f32_e32 v28, v28, v29
	s_nop 0
	v_readlane_b32 s34, v28, 63
	s_nop 1
	v_fmac_f32_e32 v27, s34, v222
	v_fmac_f32_e32 v25, s34, v222
	v_fma_f32 v26, s34, v222, v26
	v_fma_f32 v24, s34, v222, v24
	v_mul_f32_e32 v28, v25, v25
	v_mul_f32_e32 v29, v27, v27
	v_fma_f32 v21, s34, v222, v21
	v_fmac_f32_e32 v20, s34, v222
	v_fma_f32 v23, s34, v222, v23
	v_fmac_f32_e32 v22, s34, v222
	v_fmac_f32_e32 v28, v24, v24
	v_fmac_f32_e32 v29, v26, v26
	v_add_f32_e32 v34, v28, v29
	v_pk_mul_f32 v[28:29], v[22:23], v[22:23]
	v_pk_mul_f32 v[30:31], v[20:21], v[20:21]
	v_mov_b32_e32 v32, v28
	v_mov_b32_e32 v33, v30
	v_mov_b32_e32 v30, v29
	v_pk_add_f32 v[28:29], v[32:33], v[30:31]
	s_nop 0
	v_add_f32_e32 v29, v29, v34
	v_add_f32_e32 v28, v28, v29
	v_mov_b32_e32 v29, v2
	s_nop 0
	v_add_f32_dpp v28, v28, v28 row_shr:1 row_mask:0xf bank_mask:0xf bound_ctrl:1
	s_nop 1
	v_add_f32_dpp v28, v28, v28 row_shr:2 row_mask:0xf bank_mask:0xf bound_ctrl:1
	s_nop 1
	v_add_f32_dpp v28, v28, v28 row_shr:4 row_mask:0xf bank_mask:0xf bound_ctrl:1
	s_nop 1
	v_add_f32_dpp v28, v28, v28 row_shr:8 row_mask:0xf bank_mask:0xf bound_ctrl:1
	s_nop 1
	v_mov_b32_dpp v29, v28 row_bcast:15 row_mask:0xa bank_mask:0xf
	v_add_f32_e32 v28, v28, v29
	v_mov_b32_e32 v29, v2
	s_nop 1
	v_mov_b32_dpp v29, v28 row_bcast:31 row_mask:0xc bank_mask:0xf
	v_add_f32_e32 v28, v28, v29
	s_nop 0
	v_readlane_b32 s34, v28, 63
	s_nop 1
	v_fma_f32 v28, s34, v223, v159
	v_rsq_f32_e32 v28, v28
	s_mov_b64 s[34:35], 0
	v_pk_mul_f32 v[24:25], v[24:25], v[28:29] op_sel_hi:[1,0]
	v_pk_mul_f32 v[26:27], v[26:27], v[28:29] op_sel_hi:[1,0]
	v_pk_fma_f32 v[12:13], v[12:13], v[24:25], v[16:17]
	v_pk_mul_f32 v[16:17], v[20:21], v[28:29] op_sel_hi:[1,0]
	v_pk_fma_f32 v[14:15], v[14:15], v[26:27], v[18:19]
	v_pk_mul_f32 v[18:19], v[22:23], v[28:29] op_sel_hi:[1,0]
	v_pk_fma_f32 v[4:5], v[4:5], v[16:17], v[8:9]
	v_pk_fma_f32 v[6:7], v[6:7], v[18:19], v[10:11]
	v_mul_f32_e32 v9, 0xbfb8aa3b, v4
	v_exp_f32_e32 v9, v9
	v_mul_f32_e32 v10, 0xbfb8aa3b, v5
	v_mul_f32_e32 v11, 0xbfb8aa3b, v6
	v_exp_f32_e32 v10, v10
	v_exp_f32_e32 v11, v11
	v_mul_f32_e32 v8, 0xbfb8aa3b, v12
	v_add_f32_e32 v9, 1.0, v9
	v_exp_f32_e32 v8, v8
	v_rcp_f32_e32 v9, v9
	v_add_f32_e32 v10, 1.0, v10
	v_add_f32_e32 v11, 1.0, v11
	v_rcp_f32_e32 v10, v10
	v_rcp_f32_e32 v11, v11
	v_add_f32_e32 v8, 1.0, v8
	v_mul_f32_e32 v9, v4, v9
	v_mul_f32_e32 v4, 0xbfb8aa3b, v13
	v_rcp_f32_e32 v8, v8
	v_exp_f32_e32 v4, v4
	v_mul_f32_e32 v10, v5, v10
	v_mul_f32_e32 v5, 0xbfb8aa3b, v14
	v_mul_f32_e32 v11, v6, v11
	v_mul_f32_e32 v6, 0xbfb8aa3b, v15
	v_exp_f32_e32 v5, v5
	v_exp_f32_e32 v6, v6
	v_mul_f32_e32 v8, v12, v8
	v_add_f32_e32 v4, 1.0, v4
	v_mul_f32_e32 v12, 0xbfb8aa3b, v7
	v_rcp_f32_e32 v4, v4
	v_add_f32_e32 v5, 1.0, v5
	v_add_f32_e32 v6, 1.0, v6
	v_exp_f32_e32 v12, v12
	v_rcp_f32_e32 v5, v5
	v_rcp_f32_e32 v6, v6
	v_mul_f32_e32 v4, v13, v4
	v_add_f32_e32 v12, 1.0, v12
	v_mul_f32_e32 v5, v14, v5
	v_mul_f32_e32 v6, v15, v6
	v_rcp_f32_e32 v12, v12
	v_cvt_pk_bf16_f32 v4, v8, v4
	v_or_b32_e32 v8, 3, v48
	v_cvt_pk_bf16_f32 v5, v5, v6
	v_cvt_pk_bf16_f32 v6, v9, v10
	v_ashrrev_i32_e32 v9, 31, v8
	v_lshlrev_b64 v[8:9], 12, v[8:9]
	v_lshl_add_u64 v[8:9], s[26:27], 0, v[8:9]
	v_mul_f32_e32 v7, v7, v12
	v_lshl_add_u64 v[0:1], v[8:9], 0, v[0:1]
	v_cvt_pk_bf16_f32 v7, v11, v7
	global_store_dwordx4 v[0:1], v[4:7], off offset:2048 sc1
	s_barrier

.LBB0_480:
	v_mov_b32_e32 v0, s7
	v_cndmask_b32_e64 v0, v40, v0, s[38:39]
	v_cndmask_b32_e64 v40, v0, v40, s[40:41]
	v_cndmask_b32_e64 v0, v43, v227, s[44:45]
	v_max_f32_e32 v1, v61, v61
	v_max_f32_e32 v43, v44, v44
	v_max_f32_e32 v1, v43, v1
	v_max_f32_e32 v43, v3, v3
	v_max_f32_e32 v46, v45, v45
	v_max_f32_e32 v43, v46, v43
	v_max3_f32 v1, v54, v1, v43
	v_max_f32_e32 v43, v39, v39
	v_max_f32_e32 v46, v38, v38
	v_max_f32_e32 v43, v46, v43
	v_max_f32_e32 v46, v35, v35
	v_max_f32_e32 v47, v34, v34
	v_max_f32_e32 v46, v47, v46
	v_max3_f32 v43, v36, v37, v43
	v_max3_f32 v46, v32, v33, v46
	v_max3_f32 v1, v1, v43, v46
	v_max_f32_e32 v43, v31, v31
	v_max_f32_e32 v46, v30, v30
	v_max_f32_e32 v43, v46, v43
	v_max_f32_e32 v46, v27, v27
	v_max_f32_e32 v47, v26, v26
	v_max_f32_e32 v46, v47, v46
	v_max3_f32 v43, v28, v29, v43
	v_max3_f32 v46, v24, v25, v46
	v_max3_f32 v1, v1, v43, v46
	v_max_f32_e32 v43, v23, v23
	v_max_f32_e32 v46, v22, v22
	v_max_f32_e32 v43, v46, v43
	v_max_f32_e32 v46, v19, v19
	v_max_f32_e32 v47, v18, v18
	v_max_f32_e32 v46, v47, v46
	v_max3_f32 v43, v20, v21, v43
	v_max3_f32 v46, v16, v17, v46
	v_cndmask_b32_e64 v42, v42, v227, s[42:43]
	v_max3_f32 v1, v1, v43, v46
	v_max_f32_e32 v43, v15, v15
	v_max_f32_e32 v46, v14, v14
	v_max_f32_e32 v43, v46, v43
	v_max_f32_e32 v46, v0, v0
	v_max_f32_e32 v47, v42, v42
	v_cndmask_b32_e64 v41, v227, v41, s[40:41]
	v_max_f32_e32 v46, v47, v46
	v_max3_f32 v43, v12, v13, v43
	v_max3_f32 v46, v40, v41, v46
	v_max3_f32 v1, v1, v43, v46
	ds_bpermute_b32 v43, v56, v1
	s_add_i32 s34, s34, 0xc000
	v_add_u32_e32 v60, 0x900, v60
	v_add_u32_e32 v55, 1, v55
	s_cmp_lg_u32 s34, 0x3c000
	s_waitcnt lgkmcnt(0)
	v_max_f32_e32 v43, v43, v43
	v_max_f32_e32 v1, v1, v43
	ds_bpermute_b32 v43, v57, v1
	s_waitcnt lgkmcnt(0)
	v_max_f32_e32 v43, v43, v43
	v_max_f32_e32 v1, v1, v43
	v_pk_mul_f32 v[0:1], v[0:1], s[18:19] op_sel_hi:[1,0]
	s_nop 0
	v_fma_f32 v43, v44, s18, -v1
	v_exp_f32_e32 v43, v43
	v_fma_f32 v46, v61, s18, -v1
	v_exp_f32_e32 v46, v46
	v_fma_f32 v45, v45, s18, -v1
	v_exp_f32_e32 v45, v45
	v_fma_f32 v3, v3, s18, -v1
	v_exp_f32_e32 v47, v3
	v_fma_f32 v36, v36, s18, -v1
	v_add_f32_e32 v44, 0, v43
	v_exp_f32_e32 v36, v36
	v_fma_f32 v37, v37, s18, -v1
	v_add_f32_e32 v44, v46, v44
	v_exp_f32_e32 v37, v37
	v_fma_f32 v38, v38, s18, -v1
	v_add_f32_e32 v44, v45, v44
	v_exp_f32_e32 v38, v38
	v_fma_f32 v39, v39, s18, -v1
	v_add_f32_e32 v3, v47, v44
	v_exp_f32_e32 v39, v39
	v_fma_f32 v32, v32, s18, -v1
	v_add_f32_e32 v3, v36, v3
	v_exp_f32_e32 v44, v32
	v_fma_f32 v32, v33, s18, -v1
	v_add_f32_e32 v3, v37, v3
	v_exp_f32_e32 v61, v32
	v_fma_f32 v32, v34, s18, -v1
	v_add_f32_e32 v3, v38, v3
	v_exp_f32_e32 v62, v32
	v_fma_f32 v32, v35, s18, -v1
	v_add_f32_e32 v3, v39, v3
	v_exp_f32_e32 v63, v32
	v_fma_f32 v28, v28, s18, -v1
	v_add_f32_e32 v3, v44, v3
	v_exp_f32_e32 v64, v28
	v_fma_f32 v28, v29, s18, -v1
	v_add_f32_e32 v3, v61, v3
	v_exp_f32_e32 v65, v28
	v_fma_f32 v28, v30, s18, -v1
	v_add_f32_e32 v3, v62, v3
	v_exp_f32_e32 v66, v28
	v_fma_f32 v28, v31, s18, -v1
	v_add_f32_e32 v3, v63, v3
	v_exp_f32_e32 v67, v28
	v_fma_f32 v24, v24, s18, -v1
	v_add_f32_e32 v3, v64, v3
	v_exp_f32_e32 v68, v24
	v_fma_f32 v24, v25, s18, -v1
	v_add_f32_e32 v3, v65, v3
	v_exp_f32_e32 v69, v24
	v_fma_f32 v24, v26, s18, -v1
	v_add_f32_e32 v3, v66, v3
	v_exp_f32_e32 v70, v24
	v_fma_f32 v24, v27, s18, -v1
	v_add_f32_e32 v3, v67, v3
	v_exp_f32_e32 v71, v24
	v_fma_f32 v20, v20, s18, -v1
	v_add_f32_e32 v3, v68, v3
	v_exp_f32_e32 v72, v20
	v_fma_f32 v20, v21, s18, -v1
	v_add_f32_e32 v3, v69, v3
	v_exp_f32_e32 v21, v20
	v_fma_f32 v20, v22, s18, -v1
	v_add_f32_e32 v3, v70, v3
	v_exp_f32_e32 v73, v20
	v_fma_f32 v20, v23, s18, -v1
	v_add_f32_e32 v3, v71, v3
	v_exp_f32_e32 v74, v20
	v_fma_f32 v16, v16, s18, -v1
	v_add_f32_e32 v3, v72, v3
	v_exp_f32_e32 v20, v16
	v_fma_f32 v16, v17, s18, -v1
	v_add_f32_e32 v3, v21, v3
	v_exp_f32_e32 v17, v16
	v_fma_f32 v16, v18, s18, -v1
	v_add_f32_e32 v3, v73, v3
	v_exp_f32_e32 v75, v16
	v_fma_f32 v16, v19, s18, -v1
	v_add_f32_e32 v3, v74, v3
	v_exp_f32_e32 v19, v16
	v_fma_f32 v12, v12, s18, -v1
	v_add_f32_e32 v3, v20, v3
	v_exp_f32_e32 v76, v12
	v_fma_f32 v12, v13, s18, -v1
	v_add_f32_e32 v3, v17, v3
	v_exp_f32_e32 v77, v12
	v_fma_f32 v12, v14, s18, -v1
	v_add_f32_e32 v3, v75, v3
	v_exp_f32_e32 v78, v12
	v_fma_f32 v12, v15, s18, -v1
	v_add_f32_e32 v3, v19, v3
	v_exp_f32_e32 v79, v12
	v_add_f32_e32 v3, v76, v3
	v_add_f32_e32 v3, v77, v3
	v_add_f32_e32 v3, v78, v3
	v_add_f32_e32 v12, v79, v3
	v_fma_f32 v3, v40, s18, -v1
	v_exp_f32_e32 v3, v3
	v_fma_f32 v13, v41, s18, -v1
	v_exp_f32_e32 v14, v13
	v_fma_f32 v13, v42, s18, -v1
	v_exp_f32_e32 v15, v13
	v_sub_f32_e32 v0, v0, v1
	v_exp_f32_e32 v16, v0
	v_add_f32_e32 v12, v3, v12
	v_add_f32_e32 v12, v14, v12
	v_add_f32_e32 v12, v15, v12
	v_add_f32_e32 v0, v16, v12
	ds_bpermute_b32 v12, v56, v0
	v_sub_f32_e32 v1, v58, v1
	v_exp_f32_e32 v1, v1
	v_cvt_pk_bf16_f32 v22, v43, v46
	v_add_u32_e32 v46, 0x6000, v53
	s_waitcnt lgkmcnt(0)
	v_add_f32_e32 v0, v0, v12
	ds_bpermute_b32 v12, v57, v0
	v_cvt_pk_bf16_f32 v23, v45, v47
	v_cvt_pk_bf16_f32 v24, v36, v37
	v_cvt_pk_bf16_f32 v25, v38, v39
	ds_read2_b64 v[26:29], v53 offset1:4
	s_waitcnt lgkmcnt(1)
	v_add_f32_e32 v0, v0, v12
	v_add_f32_e32 v12, v1, v0
	v_add_u32_e32 v0, 0x2000, v53
	v_add_u32_e32 v1, 0x4000, v53
	ds_read2_b64 v[30:33], v0 offset0:32 offset1:36
	ds_read2_b64 v[34:37], v1 offset0:64 offset1:68
	ds_read2_b64 v[38:41], v46 offset0:96 offset1:100
	s_waitcnt lgkmcnt(3)
	v_mfma_f32_16x16x32_bf16 v[26:29], v[26:29], v[22:25], 0
	v_add_u32_e32 v13, 32, v53
	s_waitcnt lgkmcnt(2)
	v_mfma_f32_16x16x32_bf16 v[30:33], v[30:33], v[22:25], 0
	s_waitcnt lgkmcnt(1)
	v_mfma_f32_16x16x32_bf16 v[34:37], v[34:37], v[22:25], 0
	s_waitcnt lgkmcnt(0)
	v_mfma_f32_16x16x32_bf16 v[22:25], v[38:41], v[22:25], 0
	v_cvt_pk_bf16_f32 v38, v44, v61
	v_cvt_pk_bf16_f32 v39, v62, v63
	v_cvt_pk_bf16_f32 v40, v64, v65
	v_cvt_pk_bf16_f32 v41, v66, v67
	ds_read2_b64 v[42:45], v53 offset0:8 offset1:12
	s_waitcnt lgkmcnt(0)
	v_mfma_f32_16x16x32_bf16 v[26:29], v[42:45], v[38:41], v[26:29]
	ds_read2_b64 v[42:45], v0 offset0:40 offset1:44
	s_waitcnt lgkmcnt(0)
	v_mfma_f32_16x16x32_bf16 v[30:33], v[42:45], v[38:41], v[30:33]
	ds_read2_b64 v[42:45], v1 offset0:72 offset1:76
	s_waitcnt lgkmcnt(0)
	v_mfma_f32_16x16x32_bf16 v[34:37], v[42:45], v[38:41], v[34:37]
	ds_read2_b64 v[42:45], v46 offset0:104 offset1:108
	s_waitcnt lgkmcnt(0)
	v_mfma_f32_16x16x32_bf16 v[22:25], v[42:45], v[38:41], v[22:25]
	v_cvt_pk_bf16_f32 v38, v68, v69
	v_cvt_pk_bf16_f32 v39, v70, v71
	v_cvt_pk_bf16_f32 v40, v72, v21
	v_cvt_pk_bf16_f32 v41, v73, v74
	ds_read2_b64 v[42:45], v53 offset0:16 offset1:20
	s_waitcnt lgkmcnt(0)
	v_mfma_f32_16x16x32_bf16 v[26:29], v[42:45], v[38:41], v[26:29]
	ds_read2_b64 v[42:45], v0 offset0:48 offset1:52
	s_waitcnt lgkmcnt(0)
	v_mfma_f32_16x16x32_bf16 v[30:33], v[42:45], v[38:41], v[30:33]
	ds_read2_b64 v[42:45], v1 offset0:80 offset1:84
	s_waitcnt lgkmcnt(0)
	v_mfma_f32_16x16x32_bf16 v[34:37], v[42:45], v[38:41], v[34:37]
	ds_read2_b64 v[42:45], v46 offset0:112 offset1:116
	v_cvt_pk_bf16_f32 v18, v20, v17
	v_cvt_pk_bf16_f32 v19, v75, v19
	s_waitcnt lgkmcnt(0)
	v_mfma_f32_16x16x32_bf16 v[22:25], v[42:45], v[38:41], v[22:25]
	v_cvt_pk_bf16_f32 v20, v76, v77
	v_cvt_pk_bf16_f32 v21, v78, v79
	ds_read2_b64 v[38:41], v53 offset0:24 offset1:28
	s_waitcnt lgkmcnt(0)
	v_mfma_f32_16x16x32_bf16 v[26:29], v[38:41], v[18:21], v[26:29]
	ds_read2_b64 v[38:41], v0 offset0:56 offset1:60
	s_waitcnt lgkmcnt(0)
	v_mfma_f32_16x16x32_bf16 v[30:33], v[38:41], v[18:21], v[30:33]
	ds_read2_b64 v[38:41], v1 offset0:88 offset1:92
	s_waitcnt lgkmcnt(0)
	v_mfma_f32_16x16x32_bf16 v[34:37], v[38:41], v[18:21], v[34:37]
	ds_read2_b64 v[38:41], v46 offset0:120 offset1:124
	v_cvt_pk_bf16_f32 v0, v3, v14
	v_cvt_pk_bf16_f32 v1, v15, v16
	s_waitcnt lgkmcnt(0)
	v_mfma_f32_16x16x32_bf16 v[18:21], v[38:41], v[18:21], v[22:25]
	ds_read_b64 v[14:15], v53 offset:256
	s_nop 1
	ds_read_b64 v[22:23], v53 offset:8704
	v_mov_b32_e32 v3, v2
	s_waitcnt vmcnt(0)
	v_mov_b64_e32 v[42:43], v[10:11]
	v_mov_b64_e32 v[40:41], v[8:9]
	s_waitcnt lgkmcnt(1)
	v_mov_b32_e32 v16, v14
	v_mov_b32_e32 v17, v15
	s_waitcnt lgkmcnt(0)
	v_mov_b32_e32 v24, v22
	v_mov_b32_e32 v25, v23
	v_mfma_f32_16x16x32_bf16 v[14:17], v[14:17], v[0:3], v[26:29]
	s_nop 2
	ds_read_b64 v[26:27], v53 offset:17152
	v_mfma_f32_16x16x32_bf16 v[22:25], v[22:25], v[0:3], v[30:33]
	s_nop 2
	ds_read_b64 v[30:31], v53 offset:25600
	s_waitcnt lgkmcnt(1)
	v_mov_b32_e32 v28, v26
	v_mov_b32_e32 v29, v27
	v_ashrrev_i32_e32 v53, 31, v52
	s_waitcnt lgkmcnt(0)
	v_mov_b32_e32 v32, v30
	v_mov_b32_e32 v33, v31
	v_mfma_f32_16x16x32_bf16 v[26:29], v[26:29], v[0:3], v[34:37]
	s_nop 0
	v_mfma_f32_16x16x32_bf16 v[18:21], v[30:33], v[0:3], v[18:21]
	v_div_scale_f32 v0, s[36:37], v12, v12, 1.0
	v_rcp_f32_e32 v1, v0
	s_nop 0
	v_fma_f32 v3, -v0, v1, 1.0
	v_fmac_f32_e32 v1, v3, v1
	v_div_scale_f32 v3, vcc, 1.0, v12, 1.0
	v_mul_f32_e32 v30, v3, v1
	v_fma_f32 v31, -v0, v30, v3
	v_fmac_f32_e32 v30, v31, v1
	v_fma_f32 v0, -v0, v30, v3
	v_div_fmas_f32 v0, v0, v1, v30
	v_div_fixup_f32 v3, v0, v12, 1.0
	v_lshlrev_b64 v[0:1], 12, v[52:53]
	v_mul_f32_e32 v12, v3, v14
	v_mul_f32_e32 v14, v3, v15
	v_lshl_add_u64 v[0:1], v[50:51], 0, v[0:1]
	v_cvt_pk_bf16_f32 v14, v12, v14
	v_mul_f32_e32 v12, v3, v16
	v_mul_f32_e32 v15, v3, v17
	v_cvt_pk_bf16_f32 v15, v12, v15
	global_store_dwordx2 v[0:1], v[14:15], off sc1
	v_mul_f32_e32 v12, v3, v22
	v_mul_f32_e32 v14, v3, v23
	v_cvt_pk_bf16_f32 v14, v12, v14
	v_mul_f32_e32 v12, v3, v24
	v_mul_f32_e32 v15, v3, v25
	v_cvt_pk_bf16_f32 v15, v12, v15
	global_store_dwordx2 v[0:1], v[14:15], off offset:32 sc1
	v_mul_f32_e32 v12, v3, v26
	v_mul_f32_e32 v14, v3, v27
	v_cvt_pk_bf16_f32 v14, v12, v14
	v_mul_f32_e32 v12, v3, v28
	v_mul_f32_e32 v15, v3, v29
	v_cvt_pk_bf16_f32 v15, v12, v15
	global_store_dwordx2 v[0:1], v[14:15], off offset:64 sc1
	v_mul_f32_e32 v12, v3, v18
	v_mul_f32_e32 v14, v3, v19
	v_add_u32_e32 v52, 16, v52
	v_mov_b32_e32 v53, v13
	v_cvt_pk_bf16_f32 v14, v12, v14
	v_mul_f32_e32 v12, v3, v20
	v_mul_f32_e32 v3, v3, v21
	v_cvt_pk_bf16_f32 v15, v12, v3
	global_store_dwordx2 v[0:1], v[14:15], off offset:96 sc1
	s_cbranch_scc0 .LBB0_401

.LBB0_562:
	v_lshl_or_b32 v182, s64, 8, v201
	v_lshl_add_u32 v186, s96, 8, v3
	v_ashrrev_i32_e32 v183, 31, v182
	v_lshlrev_b64 v[212:213], 1, v[182:183]
	v_ashrrev_i32_e32 v187, 31, v186
	v_lshl_add_u64 v[184:185], s[20:21], 0, v[212:213]
	v_lshlrev_b64 v[214:215], 12, v[186:187]
	v_lshl_add_u64 v[116:117], v[184:185], 0, v[214:215]
	global_load_dwordx4 v[204:207], v[116:117], off
	global_load_dwordx4 v[208:211], v[116:117], off offset:256
	v_or_b32_e32 v196, 16, v186
	v_ashrrev_i32_e32 v197, 31, v196
	v_or_b32_e32 v192, 32, v186
	v_lshlrev_b64 v[198:199], 12, v[196:197]
	v_ashrrev_i32_e32 v193, 31, v192
	v_or_b32_e32 v188, 48, v186
	v_lshl_add_u64 v[116:117], v[184:185], 0, v[198:199]
	v_lshlrev_b64 v[194:195], 12, v[192:193]
	v_ashrrev_i32_e32 v189, 31, v188
	global_load_dwordx4 v[152:155], v[116:117], off
	global_load_dwordx4 v[148:151], v[116:117], off offset:256
	v_lshl_add_u64 v[116:117], v[184:185], 0, v[194:195]
	v_lshlrev_b64 v[190:191], 12, v[188:189]
	global_load_dwordx4 v[136:139], v[116:117], off
	global_load_dwordx4 v[124:127], v[116:117], off offset:256
	v_lshl_add_u64 v[116:117], v[184:185], 0, v[190:191]
	global_load_dwordx4 v[120:123], v[116:117], off
	s_nop 0
	global_load_dwordx4 v[116:119], v[116:117], off offset:256
	v_lshl_add_u64 v[214:215], s[20:21], 0, v[214:215]
	v_lshl_add_u64 v[212:213], v[214:215], 0, v[212:213]
	s_lshl_b32 s42, s64, 2
	s_ashr_i32 s43, s42, 31
	s_waitcnt vmcnt(0)
	v_lshlrev_b32_e32 v216, 16, v204
	v_and_b32_e32 v217, 0xffff0000, v204
	v_lshlrev_b32_e32 v204, 16, v205
	v_and_b32_e32 v205, 0xffff0000, v205
	v_lshlrev_b32_e32 v218, 16, v206
	v_and_b32_e32 v219, 0xffff0000, v206
	v_lshlrev_b32_e32 v206, 16, v207
	v_and_b32_e32 v207, 0xffff0000, v207
	v_pk_fma_f32 v[146:147], s[44:45], v[146:147], v[204:205]
	v_pk_fma_f32 v[144:145], s[0:1], v[144:145], v[216:217]
	v_pk_fma_f32 v[204:205], s[44:45], v[142:143], v[206:207]
	v_pk_fma_f32 v[206:207], s[0:1], v[140:141], v[218:219]
	v_cvt_pk_bf16_f32 v140, v144, v145
	v_cvt_pk_bf16_f32 v141, v146, v147
	s_nop 0
	v_cvt_pk_bf16_f32 v142, v206, v207
	v_cvt_pk_bf16_f32 v143, v204, v205
	global_store_dwordx4 v[212:213], v[140:143], off sc1
	s_nop 1
	v_mul_f32_e32 v140, v145, v145
	v_mul_f32_e32 v141, v147, v147
	v_fmac_f32_e32 v140, v144, v144
	v_fmac_f32_e32 v141, v146, v146
	v_add_f32_e32 v140, v140, v141
	v_mul_f32_e32 v141, v207, v207
	v_fmac_f32_e32 v141, v206, v206
	v_add_f32_e32 v140, v141, v140
	v_mul_f32_e32 v141, v205, v205
	v_fmac_f32_e32 v141, v204, v204
	v_add_f32_e32 v203, v141, v140
	v_lshlrev_b32_e32 v140, 16, v208
	v_and_b32_e32 v141, 0xffff0000, v208
	v_lshlrev_b32_e32 v142, 16, v209
	v_and_b32_e32 v143, 0xffff0000, v209
	v_lshlrev_b32_e32 v144, 16, v210
	v_and_b32_e32 v145, 0xffff0000, v210
	v_lshlrev_b32_e32 v146, 16, v211
	v_and_b32_e32 v147, 0xffff0000, v211
	v_pk_fma_f32 v[134:135], s[44:45], v[134:135], v[142:143]
	v_pk_fma_f32 v[132:133], s[0:1], v[132:133], v[140:141]
	v_pk_fma_f32 v[142:143], s[0:1], v[128:129], v[144:145]
	v_cvt_pk_bf16_f32 v128, v132, v133
	v_cvt_pk_bf16_f32 v129, v134, v135
	v_pk_fma_f32 v[140:141], s[44:45], v[130:131], v[146:147]
	v_cvt_pk_bf16_f32 v130, v142, v143
	s_nop 0
	v_cvt_pk_bf16_f32 v131, v140, v141
	global_store_dwordx4 v[212:213], v[128:131], off offset:256 sc1
	s_nop 1
	v_mul_f32_e32 v128, v133, v133
	v_mul_f32_e32 v129, v135, v135
	v_fmac_f32_e32 v128, v132, v132
	v_fmac_f32_e32 v129, v134, v134
	v_add_f32_e32 v128, v128, v129
	v_mul_f32_e32 v129, v143, v143
	v_fmac_f32_e32 v129, v142, v142
	v_add_f32_e32 v128, v129, v128
	v_mul_f32_e32 v129, v141, v141
	v_fmac_f32_e32 v129, v140, v140
	v_add_f32_e32 v128, v129, v128
	v_and_b32_e32 v130, 64, v221
	v_add_f32_e32 v129, v203, v128
	v_xor_b32_e32 v128, 16, v221
	v_add_u32_e32 v131, 64, v130
	v_cmp_lt_i32_e32 vcc, v128, v131
	s_nop 1
	v_cndmask_b32_e32 v128, v221, v128, vcc
	v_lshlrev_b32_e32 v128, 2, v128
	ds_bpermute_b32 v130, v128, v129
	s_waitcnt lgkmcnt(0)
	v_add_f32_e32 v130, v129, v130
	v_xor_b32_e32 v129, 32, v221
	v_cmp_lt_i32_e32 vcc, v129, v131
	s_nop 1
	v_cndmask_b32_e32 v129, v221, v129, vcc
	v_lshlrev_b32_e32 v129, 2, v129
	ds_bpermute_b32 v131, v129, v130
	s_and_saveexec_b64 s[34:35], s[38:39]
	s_cbranch_execz .LBB0_564
	v_lshlrev_b64 v[132:133], 7, v[186:187]
	v_lshl_add_u64 v[132:133], s[24:25], 0, v[132:133]
	v_lshl_add_u64 v[132:133], s[42:43], 2, v[132:133]
	s_lshl_b32 s64, s63, 2
	v_lshl_add_u64 v[132:133], v[132:133], 0, s[64:65]
	s_waitcnt lgkmcnt(0)
	v_add_f32_e32 v130, v130, v131
	global_store_dword v[132:133], v130, off
.LBB0_564:
	s_or_b64 exec, exec, s[34:35]
	v_lshlrev_b32_e32 v130, 16, v152
	s_waitcnt lgkmcnt(0)
	v_and_b32_e32 v131, 0xffff0000, v152
	v_lshlrev_b32_e32 v132, 16, v153
	v_and_b32_e32 v133, 0xffff0000, v153
	v_lshlrev_b32_e32 v134, 16, v154
	v_and_b32_e32 v135, 0xffff0000, v154
	v_pk_fma_f32 v[112:113], s[0:1], v[112:113], v[130:131]
	v_pk_fma_f32 v[114:115], s[44:45], v[114:115], v[132:133]
	v_pk_fma_f32 v[132:133], s[0:1], v[108:109], v[134:135]
	v_cvt_pk_bf16_f32 v108, v112, v113
	v_mul_f32_e32 v113, v113, v113
	v_fmac_f32_e32 v113, v112, v112
	v_mul_f32_e32 v112, v115, v115
	v_fmac_f32_e32 v112, v114, v114
	v_lshlrev_b32_e32 v140, 16, v155
	v_and_b32_e32 v141, 0xffff0000, v155
	v_add_f32_e32 v112, v113, v112
	v_mul_f32_e32 v113, v133, v133
	v_pk_fma_f32 v[130:131], s[44:45], v[110:111], v[140:141]
	v_fmac_f32_e32 v113, v132, v132
	v_add_f32_e32 v112, v113, v112
	v_mul_f32_e32 v113, v131, v131
	v_fmac_f32_e32 v113, v130, v130
	v_cvt_pk_bf16_f32 v109, v114, v115
	v_add_f32_e32 v134, v113, v112
	v_lshlrev_b32_e32 v112, 16, v148
	v_and_b32_e32 v113, 0xffff0000, v148
	v_lshlrev_b32_e32 v114, 16, v149
	v_and_b32_e32 v115, 0xffff0000, v149
	v_cvt_pk_bf16_f32 v110, v132, v133
	v_cvt_pk_bf16_f32 v111, v130, v131
	v_lshlrev_b32_e32 v130, 16, v150
	v_and_b32_e32 v131, 0xffff0000, v150
	v_pk_fma_f32 v[106:107], s[44:45], v[106:107], v[114:115]
	v_pk_fma_f32 v[104:105], s[0:1], v[104:105], v[112:113]
	v_pk_fma_f32 v[114:115], s[0:1], v[100:101], v[130:131]
	v_mul_f32_e32 v100, v105, v105
	v_mul_f32_e32 v101, v107, v107
	v_fmac_f32_e32 v100, v104, v104
	v_fmac_f32_e32 v101, v106, v106
	v_lshlrev_b32_e32 v132, 16, v151
	v_and_b32_e32 v133, 0xffff0000, v151
	v_add_f32_e32 v100, v100, v101
	v_mul_f32_e32 v101, v115, v115
	v_pk_fma_f32 v[112:113], s[44:45], v[102:103], v[132:133]
	v_fmac_f32_e32 v101, v114, v114
	v_add_f32_e32 v100, v101, v100
	v_mul_f32_e32 v101, v113, v113
	v_fmac_f32_e32 v101, v112, v112
	v_add_f32_e32 v100, v101, v100
	v_add_f32_e32 v103, v134, v100
	ds_bpermute_b32 v132, v128, v103
	v_lshl_add_u64 v[100:101], s[20:21], 0, v[198:199]
	v_lshl_add_u64 v[130:131], v[182:183], 1, v[100:101]
	global_store_dwordx4 v[130:131], v[108:111], off sc1
	v_cvt_pk_bf16_f32 v102, v104, v105
	s_waitcnt lgkmcnt(0)
	v_add_f32_e32 v100, v103, v132
	ds_bpermute_b32 v101, v129, v100
	v_cvt_pk_bf16_f32 v103, v106, v107
	v_cvt_pk_bf16_f32 v104, v114, v115
	v_cvt_pk_bf16_f32 v105, v112, v113
	global_store_dwordx4 v[130:131], v[102:105], off offset:256 sc1
	s_and_saveexec_b64 s[34:35], s[38:39]
	s_cbranch_execz .LBB0_566
	v_lshlrev_b64 v[102:103], 7, v[196:197]
	v_lshl_add_u64 v[102:103], s[24:25], 0, v[102:103]
	v_lshl_add_u64 v[102:103], s[42:43], 2, v[102:103]
	s_lshl_b32 s64, s63, 2
	v_lshl_add_u64 v[102:103], v[102:103], 0, s[64:65]
	s_waitcnt lgkmcnt(0)
	v_add_f32_e32 v100, v100, v101
	global_store_dword v[102:103], v100, off
.LBB0_566:
	s_or_b64 exec, exec, s[34:35]
	v_lshlrev_b32_e32 v100, 16, v136
	s_waitcnt lgkmcnt(0)
	v_and_b32_e32 v101, 0xffff0000, v136
	v_lshlrev_b32_e32 v102, 16, v137
	v_and_b32_e32 v103, 0xffff0000, v137
	v_lshlrev_b32_e32 v104, 16, v138
	v_and_b32_e32 v105, 0xffff0000, v138
	v_pk_fma_f32 v[96:97], s[0:1], v[96:97], v[100:101]
	v_pk_fma_f32 v[98:99], s[44:45], v[98:99], v[102:103]
	v_pk_fma_f32 v[102:103], s[0:1], v[92:93], v[104:105]
	v_cvt_pk_bf16_f32 v92, v96, v97
	v_mul_f32_e32 v97, v97, v97
	v_fmac_f32_e32 v97, v96, v96
	v_mul_f32_e32 v96, v99, v99
	v_fmac_f32_e32 v96, v98, v98
	v_lshlrev_b32_e32 v106, 16, v139
	v_and_b32_e32 v107, 0xffff0000, v139
	v_add_f32_e32 v96, v97, v96
	v_mul_f32_e32 v97, v103, v103
	v_pk_fma_f32 v[100:101], s[44:45], v[94:95], v[106:107]
	v_fmac_f32_e32 v97, v102, v102
	v_add_f32_e32 v96, v97, v96
	v_mul_f32_e32 v97, v101, v101
	v_fmac_f32_e32 v97, v100, v100
	v_cvt_pk_bf16_f32 v93, v98, v99
	v_add_f32_e32 v104, v97, v96
	v_lshlrev_b32_e32 v96, 16, v124
	v_and_b32_e32 v97, 0xffff0000, v124
	v_lshlrev_b32_e32 v98, 16, v125
	v_and_b32_e32 v99, 0xffff0000, v125
	v_cvt_pk_bf16_f32 v94, v102, v103
	v_cvt_pk_bf16_f32 v95, v100, v101
	v_lshlrev_b32_e32 v100, 16, v126
	v_and_b32_e32 v101, 0xffff0000, v126
	v_pk_fma_f32 v[90:91], s[44:45], v[90:91], v[98:99]
	v_pk_fma_f32 v[88:89], s[0:1], v[88:89], v[96:97]
	v_pk_fma_f32 v[98:99], s[0:1], v[84:85], v[100:101]
	v_mul_f32_e32 v84, v89, v89
	v_mul_f32_e32 v85, v91, v91
	v_fmac_f32_e32 v84, v88, v88
	v_fmac_f32_e32 v85, v90, v90
	v_lshlrev_b32_e32 v102, 16, v127
	v_and_b32_e32 v103, 0xffff0000, v127
	v_add_f32_e32 v84, v84, v85
	v_mul_f32_e32 v85, v99, v99
	v_pk_fma_f32 v[96:97], s[44:45], v[86:87], v[102:103]
	v_fmac_f32_e32 v85, v98, v98
	v_add_f32_e32 v84, v85, v84
	v_mul_f32_e32 v85, v97, v97
	v_fmac_f32_e32 v85, v96, v96
	v_add_f32_e32 v84, v85, v84
	v_add_f32_e32 v87, v104, v84
	ds_bpermute_b32 v102, v128, v87
	v_lshl_add_u64 v[84:85], s[20:21], 0, v[194:195]
	v_lshl_add_u64 v[100:101], v[182:183], 1, v[84:85]
	global_store_dwordx4 v[100:101], v[92:95], off sc1
	v_cvt_pk_bf16_f32 v86, v88, v89
	s_waitcnt lgkmcnt(0)
	v_add_f32_e32 v84, v87, v102
	ds_bpermute_b32 v85, v129, v84
	v_cvt_pk_bf16_f32 v87, v90, v91
	v_cvt_pk_bf16_f32 v88, v98, v99
	v_cvt_pk_bf16_f32 v89, v96, v97
	global_store_dwordx4 v[100:101], v[86:89], off offset:256 sc1
	s_and_saveexec_b64 s[34:35], s[38:39]
	s_cbranch_execz .LBB0_568
	v_lshlrev_b64 v[86:87], 7, v[192:193]
	v_lshl_add_u64 v[86:87], s[24:25], 0, v[86:87]
	v_lshl_add_u64 v[86:87], s[42:43], 2, v[86:87]
	s_lshl_b32 s64, s63, 2
	v_lshl_add_u64 v[86:87], v[86:87], 0, s[64:65]
	s_waitcnt lgkmcnt(0)
	v_add_f32_e32 v84, v84, v85
	global_store_dword v[86:87], v84, off
.LBB0_568:
	s_or_b64 exec, exec, s[34:35]
	v_lshlrev_b32_e32 v84, 16, v120
	s_waitcnt lgkmcnt(0)
	v_and_b32_e32 v85, 0xffff0000, v120
	v_lshlrev_b32_e32 v86, 16, v121
	v_and_b32_e32 v87, 0xffff0000, v121
	v_lshlrev_b32_e32 v88, 16, v122
	v_and_b32_e32 v89, 0xffff0000, v122
	v_pk_fma_f32 v[80:81], s[0:1], v[80:81], v[84:85]
	v_pk_fma_f32 v[82:83], s[44:45], v[82:83], v[86:87]
	v_pk_fma_f32 v[86:87], s[0:1], v[76:77], v[88:89]
	v_cvt_pk_bf16_f32 v76, v80, v81
	v_mul_f32_e32 v81, v81, v81
	v_fmac_f32_e32 v81, v80, v80
	v_mul_f32_e32 v80, v83, v83
	v_fmac_f32_e32 v80, v82, v82
	v_lshlrev_b32_e32 v90, 16, v123
	v_and_b32_e32 v91, 0xffff0000, v123
	v_add_f32_e32 v80, v81, v80
	v_mul_f32_e32 v81, v87, v87
	v_pk_fma_f32 v[84:85], s[44:45], v[78:79], v[90:91]
	v_fmac_f32_e32 v81, v86, v86
	v_add_f32_e32 v80, v81, v80
	v_mul_f32_e32 v81, v85, v85
	v_fmac_f32_e32 v81, v84, v84
	v_cvt_pk_bf16_f32 v77, v82, v83
	v_add_f32_e32 v88, v81, v80
	v_lshlrev_b32_e32 v80, 16, v116
	v_and_b32_e32 v81, 0xffff0000, v116
	v_lshlrev_b32_e32 v82, 16, v117
	v_and_b32_e32 v83, 0xffff0000, v117
	v_cvt_pk_bf16_f32 v78, v86, v87
	v_cvt_pk_bf16_f32 v79, v84, v85
	v_lshlrev_b32_e32 v84, 16, v118
	v_and_b32_e32 v85, 0xffff0000, v118
	v_pk_fma_f32 v[74:75], s[44:45], v[74:75], v[82:83]
	v_pk_fma_f32 v[72:73], s[0:1], v[72:73], v[80:81]
	v_pk_fma_f32 v[82:83], s[0:1], v[68:69], v[84:85]
	v_mul_f32_e32 v68, v73, v73
	v_mul_f32_e32 v69, v75, v75
	v_fmac_f32_e32 v68, v72, v72
	v_fmac_f32_e32 v69, v74, v74
	v_lshlrev_b32_e32 v86, 16, v119
	v_and_b32_e32 v87, 0xffff0000, v119
	v_add_f32_e32 v68, v68, v69
	v_mul_f32_e32 v69, v83, v83
	v_pk_fma_f32 v[80:81], s[44:45], v[70:71], v[86:87]
	v_fmac_f32_e32 v69, v82, v82
	v_add_f32_e32 v68, v69, v68
	v_mul_f32_e32 v69, v81, v81
	v_fmac_f32_e32 v69, v80, v80
	v_add_f32_e32 v68, v69, v68
	v_add_f32_e32 v71, v88, v68
	ds_bpermute_b32 v86, v128, v71
	v_lshl_add_u64 v[68:69], s[20:21], 0, v[190:191]
	v_lshl_add_u64 v[84:85], v[182:183], 1, v[68:69]
	global_store_dwordx4 v[84:85], v[76:79], off sc1
	v_cvt_pk_bf16_f32 v70, v72, v73
	s_waitcnt lgkmcnt(0)
	v_add_f32_e32 v68, v71, v86
	ds_bpermute_b32 v69, v129, v68
	v_cvt_pk_bf16_f32 v71, v74, v75
	v_cvt_pk_bf16_f32 v72, v82, v83
	v_cvt_pk_bf16_f32 v73, v80, v81
	global_store_dwordx4 v[84:85], v[70:73], off offset:256 sc1
	s_and_saveexec_b64 s[34:35], s[38:39]
	s_cbranch_execz .LBB0_570
	v_lshlrev_b64 v[70:71], 7, v[188:189]
	v_lshl_add_u64 v[70:71], s[24:25], 0, v[70:71]
	v_lshl_add_u64 v[70:71], s[42:43], 2, v[70:71]
	s_lshl_b32 s64, s63, 2
	v_lshl_add_u64 v[70:71], v[70:71], 0, s[64:65]
	s_waitcnt lgkmcnt(0)
	v_add_f32_e32 v68, v68, v69
	global_store_dword v[70:71], v68, off
.LBB0_570:
	s_or_b64 exec, exec, s[34:35]
	v_add_u32_e32 v108, 0x80, v186
	v_ashrrev_i32_e32 v109, 31, v108
	v_lshlrev_b64 v[114:115], 12, v[108:109]
	s_waitcnt lgkmcnt(0)
	v_lshl_add_u64 v[68:69], v[184:185], 0, v[114:115]
	global_load_dwordx4 v[110:113], v[68:69], off
	global_load_dwordx4 v[92:95], v[68:69], off offset:256
	v_add_u32_e32 v104, 0x90, v186
	v_ashrrev_i32_e32 v105, 31, v104
	v_add_u32_e32 v100, 0xa0, v186
	v_lshlrev_b64 v[106:107], 12, v[104:105]
	v_ashrrev_i32_e32 v101, 31, v100
	v_add_u32_e32 v96, 0xb0, v186
	v_lshl_add_u64 v[68:69], v[184:185], 0, v[106:107]
	v_lshlrev_b64 v[102:103], 12, v[100:101]
	v_ashrrev_i32_e32 v97, 31, v96
	global_load_dwordx4 v[88:91], v[68:69], off
	global_load_dwordx4 v[84:87], v[68:69], off offset:256
	v_lshl_add_u64 v[68:69], v[184:185], 0, v[102:103]
	v_lshlrev_b64 v[98:99], 12, v[96:97]
	global_load_dwordx4 v[80:83], v[68:69], off
	global_load_dwordx4 v[76:79], v[68:69], off offset:256
	v_lshl_add_u64 v[68:69], v[184:185], 0, v[98:99]
	global_load_dwordx4 v[72:75], v[68:69], off
	s_nop 0
	global_load_dwordx4 v[68:71], v[68:69], off offset:256
	v_lshl_add_u64 v[114:115], s[20:21], 0, v[114:115]
	v_lshl_add_u64 v[114:115], v[182:183], 1, v[114:115]
	s_waitcnt vmcnt(7)
	v_lshlrev_b32_e32 v116, 16, v110
	v_and_b32_e32 v117, 0xffff0000, v110
	v_lshlrev_b32_e32 v110, 16, v111
	v_and_b32_e32 v111, 0xffff0000, v111
	v_lshlrev_b32_e32 v118, 16, v112
	v_and_b32_e32 v119, 0xffff0000, v112
	v_lshlrev_b32_e32 v112, 16, v113
	v_and_b32_e32 v113, 0xffff0000, v113
	v_pk_fma_f32 v[66:67], s[44:45], v[66:67], v[110:111]
	v_pk_fma_f32 v[64:65], s[0:1], v[64:65], v[116:117]
	v_pk_fma_f32 v[110:111], s[44:45], v[62:63], v[112:113]
	v_pk_fma_f32 v[112:113], s[0:1], v[60:61], v[118:119]
	v_cvt_pk_bf16_f32 v60, v64, v65
	v_cvt_pk_bf16_f32 v61, v66, v67
	s_nop 0
	v_cvt_pk_bf16_f32 v62, v112, v113
	v_cvt_pk_bf16_f32 v63, v110, v111
	global_store_dwordx4 v[114:115], v[60:63], off sc1
	s_nop 1
	v_mul_f32_e32 v60, v65, v65
	v_mul_f32_e32 v61, v67, v67
	v_fmac_f32_e32 v60, v64, v64
	v_fmac_f32_e32 v61, v66, v66
	v_add_f32_e32 v60, v60, v61
	v_mul_f32_e32 v61, v113, v113
	v_fmac_f32_e32 v61, v112, v112
	v_add_f32_e32 v60, v61, v60
	v_mul_f32_e32 v61, v111, v111
	v_fmac_f32_e32 v61, v110, v110
	v_add_f32_e32 v110, v61, v60
	s_waitcnt vmcnt(7)
	v_lshlrev_b32_e32 v60, 16, v92
	v_and_b32_e32 v61, 0xffff0000, v92
	v_lshlrev_b32_e32 v62, 16, v93
	v_and_b32_e32 v63, 0xffff0000, v93
	v_lshlrev_b32_e32 v64, 16, v94
	v_and_b32_e32 v65, 0xffff0000, v94
	v_lshlrev_b32_e32 v66, 16, v95
	v_and_b32_e32 v67, 0xffff0000, v95
	v_pk_fma_f32 v[58:59], s[44:45], v[58:59], v[62:63]
	v_pk_fma_f32 v[56:57], s[0:1], v[56:57], v[60:61]
	v_pk_fma_f32 v[62:63], s[0:1], v[52:53], v[64:65]
	v_cvt_pk_bf16_f32 v52, v56, v57
	v_cvt_pk_bf16_f32 v53, v58, v59
	v_pk_fma_f32 v[60:61], s[44:45], v[54:55], v[66:67]
	v_cvt_pk_bf16_f32 v54, v62, v63
	s_nop 0
	v_cvt_pk_bf16_f32 v55, v60, v61
	global_store_dwordx4 v[114:115], v[52:55], off offset:256 sc1
	s_nop 1
	v_mul_f32_e32 v52, v57, v57
	v_mul_f32_e32 v53, v59, v59
	v_fmac_f32_e32 v52, v56, v56
	v_fmac_f32_e32 v53, v58, v58
	v_add_f32_e32 v52, v52, v53
	v_mul_f32_e32 v53, v63, v63
	v_fmac_f32_e32 v53, v62, v62
	v_add_f32_e32 v52, v53, v52
	v_mul_f32_e32 v53, v61, v61
	v_fmac_f32_e32 v53, v60, v60
	v_add_f32_e32 v52, v53, v52
	v_add_f32_e32 v52, v110, v52
	ds_bpermute_b32 v53, v128, v52
	s_waitcnt lgkmcnt(0)
	v_add_f32_e32 v52, v52, v53
	ds_bpermute_b32 v53, v129, v52
	s_and_saveexec_b64 s[34:35], s[38:39]
	s_cbranch_execz .LBB0_572
	v_lshlrev_b64 v[54:55], 7, v[108:109]
	v_lshl_add_u64 v[54:55], s[24:25], 0, v[54:55]
	v_lshl_add_u64 v[54:55], s[42:43], 2, v[54:55]
	s_lshl_b32 s64, s63, 2
	v_lshl_add_u64 v[54:55], v[54:55], 0, s[64:65]
	s_waitcnt lgkmcnt(0)
	v_add_f32_e32 v52, v52, v53
	global_store_dword v[54:55], v52, off
.LBB0_572:
	s_or_b64 exec, exec, s[34:35]
	s_waitcnt vmcnt(7)
	v_lshlrev_b32_e32 v52, 16, v88
	s_waitcnt lgkmcnt(0)
	v_and_b32_e32 v53, 0xffff0000, v88
	v_lshlrev_b32_e32 v54, 16, v89
	v_and_b32_e32 v55, 0xffff0000, v89
	v_lshlrev_b32_e32 v56, 16, v90
	v_and_b32_e32 v57, 0xffff0000, v90
	v_pk_fma_f32 v[48:49], s[0:1], v[48:49], v[52:53]
	v_pk_fma_f32 v[50:51], s[44:45], v[50:51], v[54:55]
	v_pk_fma_f32 v[54:55], s[0:1], v[44:45], v[56:57]
	v_cvt_pk_bf16_f32 v44, v48, v49
	v_mul_f32_e32 v49, v49, v49
	v_fmac_f32_e32 v49, v48, v48
	v_mul_f32_e32 v48, v51, v51
	v_fmac_f32_e32 v48, v50, v50
	v_lshlrev_b32_e32 v58, 16, v91
	v_and_b32_e32 v59, 0xffff0000, v91
	v_add_f32_e32 v48, v49, v48
	v_mul_f32_e32 v49, v55, v55
	v_pk_fma_f32 v[52:53], s[44:45], v[46:47], v[58:59]
	v_fmac_f32_e32 v49, v54, v54
	v_add_f32_e32 v48, v49, v48
	v_mul_f32_e32 v49, v53, v53
	v_fmac_f32_e32 v49, v52, v52
	v_cvt_pk_bf16_f32 v45, v50, v51
	v_add_f32_e32 v56, v49, v48
	s_waitcnt vmcnt(6)
	v_lshlrev_b32_e32 v48, 16, v84
	v_and_b32_e32 v49, 0xffff0000, v84
	v_lshlrev_b32_e32 v50, 16, v85
	v_and_b32_e32 v51, 0xffff0000, v85
	v_cvt_pk_bf16_f32 v46, v54, v55
	v_cvt_pk_bf16_f32 v47, v52, v53
	v_lshlrev_b32_e32 v52, 16, v86
	v_and_b32_e32 v53, 0xffff0000, v86
	v_pk_fma_f32 v[42:43], s[44:45], v[42:43], v[50:51]
	v_pk_fma_f32 v[40:41], s[0:1], v[40:41], v[48:49]
	v_pk_fma_f32 v[50:51], s[0:1], v[36:37], v[52:53]
	v_mul_f32_e32 v36, v41, v41
	v_mul_f32_e32 v37, v43, v43
	v_fmac_f32_e32 v36, v40, v40
	v_fmac_f32_e32 v37, v42, v42
	v_lshlrev_b32_e32 v54, 16, v87
	v_and_b32_e32 v55, 0xffff0000, v87
	v_add_f32_e32 v36, v36, v37
	v_mul_f32_e32 v37, v51, v51
	v_pk_fma_f32 v[48:49], s[44:45], v[38:39], v[54:55]
	v_fmac_f32_e32 v37, v50, v50
	v_add_f32_e32 v36, v37, v36
	v_mul_f32_e32 v37, v49, v49
	v_fmac_f32_e32 v37, v48, v48
	v_add_f32_e32 v36, v37, v36
	v_add_f32_e32 v39, v56, v36
	ds_bpermute_b32 v54, v128, v39
	v_lshl_add_u64 v[36:37], s[20:21], 0, v[106:107]
	v_lshl_add_u64 v[52:53], v[182:183], 1, v[36:37]
	global_store_dwordx4 v[52:53], v[44:47], off sc1
	v_cvt_pk_bf16_f32 v38, v40, v41
	s_waitcnt lgkmcnt(0)
	v_add_f32_e32 v36, v39, v54
	ds_bpermute_b32 v37, v129, v36
	v_cvt_pk_bf16_f32 v39, v42, v43
	v_cvt_pk_bf16_f32 v40, v50, v51
	v_cvt_pk_bf16_f32 v41, v48, v49
	global_store_dwordx4 v[52:53], v[38:41], off offset:256 sc1
	s_and_saveexec_b64 s[34:35], s[38:39]
	s_cbranch_execz .LBB0_574
	v_lshlrev_b64 v[38:39], 7, v[104:105]
	v_lshl_add_u64 v[38:39], s[24:25], 0, v[38:39]
	v_lshl_add_u64 v[38:39], s[42:43], 2, v[38:39]
	s_lshl_b32 s64, s63, 2
	v_lshl_add_u64 v[38:39], v[38:39], 0, s[64:65]
	s_waitcnt lgkmcnt(0)
	v_add_f32_e32 v36, v36, v37
	global_store_dword v[38:39], v36, off
.LBB0_574:
	s_or_b64 exec, exec, s[34:35]
	s_waitcnt vmcnt(7)
	v_lshlrev_b32_e32 v36, 16, v80
	s_waitcnt lgkmcnt(0)
	v_and_b32_e32 v37, 0xffff0000, v80
	v_lshlrev_b32_e32 v38, 16, v81
	v_and_b32_e32 v39, 0xffff0000, v81
	v_lshlrev_b32_e32 v40, 16, v82
	v_and_b32_e32 v41, 0xffff0000, v82
	v_pk_fma_f32 v[32:33], s[0:1], v[32:33], v[36:37]
	v_pk_fma_f32 v[34:35], s[44:45], v[34:35], v[38:39]
	v_pk_fma_f32 v[38:39], s[0:1], v[28:29], v[40:41]
	v_cvt_pk_bf16_f32 v28, v32, v33
	v_mul_f32_e32 v33, v33, v33
	v_fmac_f32_e32 v33, v32, v32
	v_mul_f32_e32 v32, v35, v35
	v_fmac_f32_e32 v32, v34, v34
	v_lshlrev_b32_e32 v42, 16, v83
	v_and_b32_e32 v43, 0xffff0000, v83
	v_add_f32_e32 v32, v33, v32
	v_mul_f32_e32 v33, v39, v39
	v_pk_fma_f32 v[36:37], s[44:45], v[30:31], v[42:43]
	v_fmac_f32_e32 v33, v38, v38
	v_add_f32_e32 v32, v33, v32
	v_mul_f32_e32 v33, v37, v37
	v_fmac_f32_e32 v33, v36, v36
	v_cvt_pk_bf16_f32 v29, v34, v35
	v_add_f32_e32 v40, v33, v32
	s_waitcnt vmcnt(6)
	v_lshlrev_b32_e32 v32, 16, v76
	v_and_b32_e32 v33, 0xffff0000, v76
	v_lshlrev_b32_e32 v34, 16, v77
	v_and_b32_e32 v35, 0xffff0000, v77
	v_cvt_pk_bf16_f32 v30, v38, v39
	v_cvt_pk_bf16_f32 v31, v36, v37
	v_lshlrev_b32_e32 v36, 16, v78
	v_and_b32_e32 v37, 0xffff0000, v78
	v_pk_fma_f32 v[26:27], s[44:45], v[26:27], v[34:35]
	v_pk_fma_f32 v[24:25], s[0:1], v[24:25], v[32:33]
	v_pk_fma_f32 v[34:35], s[0:1], v[20:21], v[36:37]
	v_mul_f32_e32 v20, v25, v25
	v_mul_f32_e32 v21, v27, v27
	v_fmac_f32_e32 v20, v24, v24
	v_fmac_f32_e32 v21, v26, v26
	v_lshlrev_b32_e32 v38, 16, v79
	v_and_b32_e32 v39, 0xffff0000, v79
	v_add_f32_e32 v20, v20, v21
	v_mul_f32_e32 v21, v35, v35
	v_pk_fma_f32 v[32:33], s[44:45], v[22:23], v[38:39]
	v_fmac_f32_e32 v21, v34, v34
	v_add_f32_e32 v20, v21, v20
	v_mul_f32_e32 v21, v33, v33
	v_fmac_f32_e32 v21, v32, v32
	v_add_f32_e32 v20, v21, v20
	v_add_f32_e32 v23, v40, v20
	ds_bpermute_b32 v38, v128, v23
	v_lshl_add_u64 v[20:21], s[20:21], 0, v[102:103]
	v_lshl_add_u64 v[36:37], v[182:183], 1, v[20:21]
	global_store_dwordx4 v[36:37], v[28:31], off sc1
	v_cvt_pk_bf16_f32 v22, v24, v25
	s_waitcnt lgkmcnt(0)
	v_add_f32_e32 v20, v23, v38
	ds_bpermute_b32 v21, v129, v20
	v_cvt_pk_bf16_f32 v23, v26, v27
	v_cvt_pk_bf16_f32 v24, v34, v35
	v_cvt_pk_bf16_f32 v25, v32, v33
	global_store_dwordx4 v[36:37], v[22:25], off offset:256 sc1
	s_and_saveexec_b64 s[34:35], s[38:39]
	s_cbranch_execz .LBB0_576
	v_lshlrev_b64 v[22:23], 7, v[100:101]
	v_lshl_add_u64 v[22:23], s[24:25], 0, v[22:23]
	v_lshl_add_u64 v[22:23], s[42:43], 2, v[22:23]
	s_lshl_b32 s64, s63, 2
	v_lshl_add_u64 v[22:23], v[22:23], 0, s[64:65]
	s_waitcnt lgkmcnt(0)
	v_add_f32_e32 v20, v20, v21
	global_store_dword v[22:23], v20, off
.LBB0_576:
	s_or_b64 exec, exec, s[34:35]
	s_waitcnt vmcnt(7)
	v_lshlrev_b32_e32 v20, 16, v72
	s_waitcnt lgkmcnt(0)
	v_and_b32_e32 v21, 0xffff0000, v72
	v_lshlrev_b32_e32 v22, 16, v73
	v_and_b32_e32 v23, 0xffff0000, v73
	v_lshlrev_b32_e32 v24, 16, v74
	v_and_b32_e32 v25, 0xffff0000, v74
	v_pk_fma_f32 v[16:17], s[0:1], v[16:17], v[20:21]
	v_pk_fma_f32 v[18:19], s[44:45], v[18:19], v[22:23]
	v_pk_fma_f32 v[22:23], s[0:1], v[12:13], v[24:25]
	v_cvt_pk_bf16_f32 v12, v16, v17
	v_mul_f32_e32 v17, v17, v17
	v_fmac_f32_e32 v17, v16, v16
	v_mul_f32_e32 v16, v19, v19
	v_fmac_f32_e32 v16, v18, v18
	v_lshlrev_b32_e32 v26, 16, v75
	v_and_b32_e32 v27, 0xffff0000, v75
	v_add_f32_e32 v16, v17, v16
	v_mul_f32_e32 v17, v23, v23
	v_pk_fma_f32 v[20:21], s[44:45], v[14:15], v[26:27]
	v_fmac_f32_e32 v17, v22, v22
	v_add_f32_e32 v16, v17, v16
	v_mul_f32_e32 v17, v21, v21
	v_fmac_f32_e32 v17, v20, v20
	v_cvt_pk_bf16_f32 v13, v18, v19
	v_add_f32_e32 v24, v17, v16
	s_waitcnt vmcnt(6)
	v_lshlrev_b32_e32 v16, 16, v68
	v_and_b32_e32 v17, 0xffff0000, v68
	v_lshlrev_b32_e32 v18, 16, v69
	v_and_b32_e32 v19, 0xffff0000, v69
	v_cvt_pk_bf16_f32 v14, v22, v23
	v_cvt_pk_bf16_f32 v15, v20, v21
	v_lshlrev_b32_e32 v20, 16, v70
	v_and_b32_e32 v21, 0xffff0000, v70
	v_pk_fma_f32 v[10:11], s[44:45], v[10:11], v[18:19]
	v_pk_fma_f32 v[8:9], s[0:1], v[8:9], v[16:17]
	v_pk_fma_f32 v[18:19], s[0:1], v[4:5], v[20:21]
	v_mul_f32_e32 v4, v9, v9
	v_mul_f32_e32 v5, v11, v11
	v_fmac_f32_e32 v4, v8, v8
	v_fmac_f32_e32 v5, v10, v10
	v_lshlrev_b32_e32 v22, 16, v71
	v_and_b32_e32 v23, 0xffff0000, v71
	v_add_f32_e32 v4, v4, v5
	v_mul_f32_e32 v5, v19, v19
	v_pk_fma_f32 v[16:17], s[44:45], v[6:7], v[22:23]
	v_fmac_f32_e32 v5, v18, v18
	v_add_f32_e32 v4, v5, v4
	v_mul_f32_e32 v5, v17, v17
	v_fmac_f32_e32 v5, v16, v16
	v_add_f32_e32 v4, v5, v4
	v_add_f32_e32 v7, v24, v4
	ds_bpermute_b32 v22, v128, v7
	v_lshl_add_u64 v[4:5], s[20:21], 0, v[98:99]
	v_lshl_add_u64 v[20:21], v[182:183], 1, v[4:5]
	global_store_dwordx4 v[20:21], v[12:15], off sc1
	v_cvt_pk_bf16_f32 v6, v8, v9
	s_waitcnt lgkmcnt(0)
	v_add_f32_e32 v4, v7, v22
	ds_bpermute_b32 v5, v129, v4
	v_cvt_pk_bf16_f32 v7, v10, v11
	v_cvt_pk_bf16_f32 v8, v18, v19
	v_cvt_pk_bf16_f32 v9, v16, v17
	global_store_dwordx4 v[20:21], v[6:9], off offset:256 sc1
	s_and_saveexec_b64 s[34:35], s[38:39]
	s_cbranch_execz .LBB0_578
	v_lshlrev_b64 v[6:7], 7, v[96:97]
	v_lshl_add_u64 v[6:7], s[24:25], 0, v[6:7]
	v_lshl_add_u64 v[6:7], s[42:43], 2, v[6:7]
	s_lshl_b32 s64, s63, 2
	v_lshl_add_u64 v[6:7], v[6:7], 0, s[64:65]
	s_waitcnt lgkmcnt(0)
	v_add_f32_e32 v4, v4, v5
	global_store_dword v[6:7], v4, off
